# LN+logit / router phases: wave_sum butterflies through DPP and permlane swaps instead of ds_bpermute (same partner lanes and add order), dead address code removed
# speedup vs baseline: 1.0084x; 1.0084x over previous
; __device__ __forceinline__ int mk_tid(int wv) { return (wv << 6) | lane_now(); }
; #define LAS __attribute__((address_space(3)))
; template <int SEL> __global__ void __launch_bounds__(NWAVES * 64, 2) fwd_kernel(Args args) {
;     extern __shared__ __attribute__((aligned(16))) unsigned char lds[];
;     LAS unsigned char* ldsp = (LAS unsigned char*)lds;
;     const int G = gridDim.x, bx = blockIdx.x; const int vcu = (G % 8 == 0) ? (bx % 8) * (G / 8) + bx / 8 : bx;
;     const int wv = __builtin_amdgcn_readfirstlane((int)threadIdx.x >> 6);
;     if constexpr (SEL < 0) { const int t0_ = mk_tid(wv); if (t0_ < 2) ((volatile LAS unsigned*)(ldsp + attn_body::LDS_BYTES))[t0_] = 0u; __syncthreads();
_Z10fwd_kernelILin1EEv4Args:
	s_mov_b32 s98, 0xffff0000
	s_mov_b32 s99, 0xffff0000
	s_mov_b32 s100, 0
	s_mov_b32 s101, -1
	s_load_dword s33, s[0:1], 0xc8
	s_add_u32 s24, s0, 0xc8
	s_addc_u32 s25, s1, 0
	s_mov_b32 s76, s2
	s_waitcnt lgkmcnt(0)
	s_and_b32 s3, s33, 7
	s_cmp_lg_u32 s3, 0
	s_cbranch_scc1 .LBB0_2
	s_ashr_i32 s4, s2, 31
	s_lshr_b32 s4, s4, 29
	s_add_i32 s4, s2, s4
	s_and_b32 s5, s4, -8
	s_ashr_i32 s3, s33, 3
	s_sub_i32 s5, s2, s5
	s_mul_i32 s3, s3, s5
	s_ashr_i32 s4, s4, 3
	s_add_i32 s76, s3, s4

; __device__ __forceinline__ float shx(float v, int o) { const int l = lane_now(); return __int_as_float(__builtin_amdgcn_ds_bpermute((l ^ o) << 2, __float_as_int(v))); }
; __device__ __forceinline__ float wave_sum(float v) {
; #pragma unroll
;     for (int o = 1; o < 64; o <<= 1) v += shx(v, o);
;     return v;
; }
; template <int SRC, int EXTRA, bool OUT8 = false> ...
;     ...
;         float s = 0.f;
; #pragma unroll
;         for (int j = 0; j < 4; ++j) s += (v[j].x + v[j].y) + (v[j].z + v[j].w);
;         const float mean = wave_sum(s) * (1.f / 1024.f); float s2 = 0.f;
; #pragma unroll
;         for (int j = 0; j < 4; ++j) { v[j] = v[j] - mean; s2 += (v[j].x * v[j].x + v[j].y * v[j].y) + (v[j].z * v[j].z + v[j].w * v[j].w); }
;         const float rstd = 1.f / sqrtf(wave_sum(s2) * (1.f / 1024.f) + LN_EPS);
.LBB0_59:
	global_load_dwordx4 v[46:49], v[60:61], off offset:-3072
	global_load_dwordx4 v[42:45], v[60:61], off offset:-2048
	global_load_dwordx4 v[38:41], v[60:61], off offset:-1024
	s_waitcnt lgkmcnt(0)
	global_load_dwordx4 v[34:37], v[60:61], off
	s_waitcnt vmcnt(3)
	v_mov_b32_e32 v64, v47
	v_mov_b32_e32 v65, v48
	v_mov_b32_e32 v66, v46
	v_mov_b32_e32 v67, v49
	s_waitcnt vmcnt(2)
	v_mov_b32_e32 v74, v43
	v_mov_b32_e32 v75, v44
	v_mov_b32_e32 v76, v42
	v_mov_b32_e32 v77, v45
	v_pk_add_f32 v[64:65], v[64:65], v[66:67]
	v_pk_add_f32 v[66:67], v[74:75], v[76:77]
	v_add_f32_e32 v63, v64, v65
	v_pk_add_f32 v[64:65], v[66:67], v[66:67] op_sel:[0,1] op_sel_hi:[1,0]
	s_waitcnt vmcnt(1)
	v_add_f32_e32 v78, v38, v39
	v_add_f32_e32 v80, v40, v41
	s_waitcnt vmcnt(0)
	v_mov_b32_e32 v83, v34
	v_mov_b32_e32 v79, v36
	v_mov_b32_e32 v81, v37
	v_add_f32_e32 v82, 0, v63
	v_mov_b32_e32 v65, v35
	v_pk_add_f32 v[74:75], v[78:79], v[80:81]
	v_pk_add_f32 v[64:65], v[82:83], v[64:65]
	v_pk_add_f32 v[64:65], v[64:65], v[74:75]
	v_add_f32_e32 v63, v64, v65
	s_nop 1
	v_mov_b32_dpp v52, v63 quad_perm:[1,0,3,2] row_mask:0xf bank_mask:0xf
	v_add_f32_e32 v52, v63, v52
	s_nop 1
	v_mov_b32_dpp v63, v52 quad_perm:[2,3,0,1] row_mask:0xf bank_mask:0xf
	v_add_f32_e32 v52, v52, v63
	s_nop 1
	v_mov_b32_dpp v63, v52 row_shl:4 row_mask:0xf bank_mask:0x5
	v_mov_b32_dpp v63, v52 row_shr:4 row_mask:0xf bank_mask:0xa
	v_add_f32_e32 v52, v52, v63
	s_nop 1
	v_mov_b32_dpp v63, v52 row_ror:8 row_mask:0xf bank_mask:0xf
	v_add_f32_e32 v52, v52, v63
	v_mov_b32_e32 v63, v52
	v_mov_b32_e32 v120, v52
	s_nop 1
	v_permlane16_swap_b32_e32 v63, v120
	v_cndmask_b32_e64 v63, v120, v63, s[98:99]
	v_add_f32_e32 v52, v52, v63
	v_mov_b32_e32 v63, v52
	v_mov_b32_e32 v120, v52
	s_nop 1
	v_permlane32_swap_b32_e32 v63, v120
	v_cndmask_b32_e64 v63, v120, v63, s[100:101]
	v_add_f32_e32 v63, v52, v63
	v_fmamk_f32 v67, v63, 0xba800000, v49
	v_fmamk_f32 v47, v63, 0xba800000, v47
	v_fmamk_f32 v45, v63, 0xba800000, v45
	v_fmamk_f32 v43, v63, 0xba800000, v43
	v_fmamk_f32 v66, v63, 0xba800000, v48
	v_fmac_f32_e32 v46, 0xba800000, v63
	v_fmamk_f32 v44, v63, 0xba800000, v44
	v_fmac_f32_e32 v42, 0xba800000, v63
	v_fmamk_f32 v65, v63, 0xba800000, v41
	v_fmamk_f32 v64, v63, 0xba800000, v40
	v_fmamk_f32 v39, v63, 0xba800000, v39
	v_fmamk_f32 v49, v63, 0xba800000, v37
	v_fmamk_f32 v48, v63, 0xba800000, v36
	v_mul_f32_e32 v36, v47, v47
	v_mul_f32_e32 v37, v67, v67
	v_mul_f32_e32 v40, v43, v43
	v_mul_f32_e32 v41, v45, v45
	v_fmac_f32_e32 v38, 0xba800000, v63
	v_fmamk_f32 v35, v63, 0xba800000, v35
	v_mul_f32_e32 v52, v39, v39
	v_mul_f32_e32 v74, v65, v65
	v_fmac_f32_e32 v36, v46, v46
	v_fmac_f32_e32 v37, v66, v66
	v_fmac_f32_e32 v40, v42, v42
	v_fmac_f32_e32 v41, v44, v44
	v_fmac_f32_e32 v34, 0xba800000, v63
	v_mul_f32_e32 v75, v35, v35
	v_mul_f32_e32 v76, v49, v49
	v_fmac_f32_e32 v52, v38, v38
	v_fmac_f32_e32 v74, v64, v64
	v_add_f32_e32 v36, v36, v37
	v_add_f32_e32 v37, v40, v41
	v_fmac_f32_e32 v75, v34, v34
	v_fmac_f32_e32 v76, v48, v48
	v_add_f32_e32 v40, v52, v74
	v_add_f32_e32 v36, v36, v37
	v_add_f32_e32 v41, v75, v76
	v_add_f32_e32 v36, v40, v36
	v_add_f32_e32 v36, v41, v36
	s_nop 1
	v_mov_b32_dpp v37, v36 quad_perm:[1,0,3,2] row_mask:0xf bank_mask:0xf
	v_add_f32_e32 v36, v36, v37
	s_nop 1
	v_mov_b32_dpp v37, v36 quad_perm:[2,3,0,1] row_mask:0xf bank_mask:0xf
	v_add_f32_e32 v36, v36, v37
	s_nop 1
	v_mov_b32_dpp v37, v36 row_shl:4 row_mask:0xf bank_mask:0x5
	v_mov_b32_dpp v37, v36 row_shr:4 row_mask:0xf bank_mask:0xa
	v_add_f32_e32 v36, v36, v37
	s_nop 1
	v_mov_b32_dpp v37, v36 row_ror:8 row_mask:0xf bank_mask:0xf
	v_add_f32_e32 v36, v36, v37
	v_mov_b32_e32 v37, v36
	v_mov_b32_e32 v120, v36
	s_nop 1
	v_permlane16_swap_b32_e32 v37, v120
	v_cndmask_b32_e64 v37, v120, v37, s[98:99]
	v_add_f32_e32 v36, v36, v37
	v_mov_b32_e32 v37, v36
	v_mov_b32_e32 v120, v36
	s_nop 1
	v_permlane32_swap_b32_e32 v37, v120
	v_cndmask_b32_e64 v37, v120, v37, s[100:101]
	v_add_f32_e32 v36, v36, v37
	v_fmamk_f32 v36, v36, 0x3a800000, v51
	v_mul_f32_e32 v37, 0x4f800000, v36
	v_cmp_gt_f32_e32 vcc, s31, v36
	s_nop 1
	v_cndmask_b32_e32 v36, v36, v37, vcc
	v_sqrt_f32_e32 v37, v36
	s_nop 0
	v_add_u32_e32 v40, -1, v37
	v_add_u32_e32 v41, 1, v37
	v_fma_f32 v52, -v40, v37, v36
	v_fma_f32 v73, -v41, v37, v36
	v_cmp_ge_f32_e64 s[22:23], 0, v52
	s_nop 1
	v_cndmask_b32_e64 v37, v37, v40, s[22:23]
	v_cmp_lt_f32_e64 s[22:23], 0, v73
	s_nop 1
	v_cndmask_b32_e64 v37, v37, v41, s[22:23]
	v_mul_f32_e32 v40, 0x37800000, v37
	v_cndmask_b32_e32 v37, v37, v40, vcc
	v_cmp_class_f32_e32 vcc, v36, v68
	s_nop 1
	v_cndmask_b32_e32 v36, v37, v36, vcc
	v_div_scale_f32 v37, s[22:23], v36, v36, 1.0
	v_rcp_f32_e32 v40, v37
	v_div_scale_f32 v41, vcc, 1.0, v36, 1.0
	v_fma_f32 v52, -v37, v40, 1.0
	v_fmac_f32_e32 v40, v52, v40
	v_mul_f32_e32 v52, v41, v40
	v_fma_f32 v73, -v37, v52, v41
	v_fmac_f32_e32 v52, v73, v40
	v_fma_f32 v37, -v37, v52, v41
	v_div_fmas_f32 v37, v37, v40, v52
	v_div_fixup_f32 v52, v37, v36, 1.0
	s_and_saveexec_b64 s[22:23], s[4:5]
	s_cbranch_execz .LBB0_61
	s_ashr_i32 s27, s26, 31
	s_lshl_b64 s[42:43], s[26:27], 2
	s_add_u32 s42, s3, s42
	v_mul_f32_e32 v36, 0x3a800000, v63
	s_addc_u32 s43, s44, s43
	v_mov_b32_e32 v37, v52
	global_store_dwordx2 v53, v[36:37], s[42:43]
; __device__ __forceinline__ float shx(float v, int o) { const int l = lane_now(); return __int_as_float(__builtin_amdgcn_ds_bpermute((l ^ o) << 2, __float_as_int(v))); }
; #define LAS __attribute__((address_space(3)))
; __device__ __forceinline__ unsigned pk2(float lo, float hi) { return f2bf(lo) | (f2bf(hi) << 16); }
; __device__ __forceinline__ float wave_sum(float v) {
; #pragma unroll
;     for (int o = 1; o < 64; o <<= 1) v += shx(v, o);
;     return v;
; }
; template <int SRC, int EXTRA, bool OUT8 = false> ...
;     ...
;         for (int j = 0; j < 4; ++j) { v[j] = v[j] * rstd * gv[j] + bv[j]; if (of32) *(f32x4*)(of32 + (size_t)row * 1024 + 256 * j + 4 * lane) = v[j];
;             if (obf) { if constexpr (OUT8) { int w = 0; w = __builtin_amdgcn_cvt_pk_fp8_f32(v[j].x, v[j].y, w, false); w = __builtin_amdgcn_cvt_pk_fp8_f32(v[j].z, v[j].w, w, true); *(unsigned*)((unsigned char*)obf + (size_t)row * 1024 + 256 * j + 4 * lane) = (unsigned)w; }
;                 else { v2u o; o.x = pk2(v[j].x, v[j].y); o.y = pk2(v[j].z, v[j].w); *(v2u*)(obf + (size_t)row * 1024 + 256 * j + 4 * lane) = o; } } }
;         if (EXTRA != 0) {
;             float d[8];
; #pragma unroll
;             for (int e = 0; e < 8; ++e) { float a = 0.f;
; #pragma unroll
;                 for (int j = 0; j < 4; ++j) { const f32x4 w = *(const LAS f32x4*)(w8s + e * 1024 + 256 * j + 4 * lane); a += (v[j].x * w.x + v[j].y * w.y) + (v[j].z * w.z + v[j].w * w.w); }
;                 d[e] = wave_sum(a); }
.LBB0_61:
	s_or_b64 exec, exec, s[22:23]
	v_pk_mul_f32 v[40:41], v[46:47], v[52:53] op_sel_hi:[1,0]
	v_pk_mul_f32 v[36:37], v[66:67], v[52:53] op_sel_hi:[1,0]
	v_pk_fma_f32 v[40:41], v[2:3], v[40:41], v[10:11]
	v_pk_fma_f32 v[36:37], v[4:5], v[36:37], v[12:13]
	v_bfe_u32 v46, v40, 16, 1
	v_add3_u32 v46, v40, v46, s35
	v_bfe_u32 v47, v41, 16, 1
	v_lshrrev_b32_e32 v46, 16, v46
	v_add3_u32 v47, v41, v47, s35
	v_and_or_b32 v46, v47, s46, v46
	v_bfe_u32 v47, v36, 16, 1
	v_add3_u32 v47, v36, v47, s35
	v_bfe_u32 v63, v37, 16, 1
	v_lshrrev_b32_e32 v47, 16, v47
	v_add3_u32 v63, v37, v63, s35
	v_and_or_b32 v47, v63, s46, v47
	global_store_dwordx2 v[58:59], v[46:47], off
	v_pk_mul_f32 v[44:45], v[44:45], v[52:53] op_sel_hi:[1,0]
	v_pk_mul_f32 v[46:47], v[42:43], v[52:53] op_sel_hi:[1,0]
	v_pk_fma_f32 v[42:43], v[8:9], v[44:45], v[16:17]
	v_pk_fma_f32 v[44:45], v[6:7], v[46:47], v[14:15]
	v_bfe_u32 v63, v43, 16, 1
	v_bfe_u32 v46, v44, 16, 1
	v_add3_u32 v46, v44, v46, s35
	v_bfe_u32 v47, v45, 16, 1
	v_lshrrev_b32_e32 v46, 16, v46
	v_add3_u32 v47, v45, v47, s35
	v_and_or_b32 v46, v47, s46, v46
	v_bfe_u32 v47, v42, 16, 1
	v_add3_u32 v47, v42, v47, s35
	v_lshrrev_b32_e32 v47, 16, v47
	v_add3_u32 v63, v43, v63, s35
	v_and_or_b32 v47, v63, s46, v47
	global_store_dwordx2 v[58:59], v[46:47], off offset:512
	v_pk_mul_f32 v[46:47], v[64:65], v[52:53] op_sel_hi:[1,0]
	v_pk_mul_f32 v[64:65], v[38:39], v[52:53] op_sel_hi:[1,0]
	v_pk_fma_f32 v[38:39], v[20:21], v[46:47], v[28:29]
	v_pk_fma_f32 v[46:47], v[18:19], v[64:65], v[26:27]
	v_bfe_u32 v65, v39, 16, 1
	v_bfe_u32 v63, v46, 16, 1
	v_add3_u32 v63, v46, v63, s35
	v_bfe_u32 v64, v47, 16, 1
	v_lshrrev_b32_e32 v63, 16, v63
	v_add3_u32 v64, v47, v64, s35
	v_and_or_b32 v64, v64, s46, v63
	v_bfe_u32 v63, v38, 16, 1
	v_add3_u32 v63, v38, v63, s35
	v_lshrrev_b32_e32 v63, 16, v63
	v_add3_u32 v65, v39, v65, s35
	v_and_or_b32 v65, v65, s46, v63
	global_store_dwordx2 v[58:59], v[64:65], off offset:1024
	v_pk_mul_f32 v[48:49], v[48:49], v[52:53] op_sel_hi:[1,0]
	v_pk_mul_f32 v[64:65], v[34:35], v[52:53] op_sel_hi:[1,0]
	v_pk_fma_f32 v[34:35], v[24:25], v[48:49], v[32:33]
	v_pk_fma_f32 v[48:49], v[22:23], v[64:65], v[30:31]
	v_bfe_u32 v73, v35, 16, 1
	v_bfe_u32 v52, v48, 16, 1
	v_add3_u32 v52, v48, v52, s35
	v_bfe_u32 v63, v49, 16, 1
	v_lshrrev_b32_e32 v52, 16, v52
	v_add3_u32 v63, v49, v63, s35
	v_and_or_b32 v74, v63, s46, v52
	v_bfe_u32 v52, v34, 16, 1
	v_add3_u32 v52, v34, v52, s35
	v_lshrrev_b32_e32 v63, 16, v52
	v_add_u32_e32 v52, 0, v50
	ds_read_b128 v[64:67], v52
	v_add3_u32 v73, v35, v73, s35
	v_and_or_b32 v75, v73, s46, v63
	global_store_dwordx2 v[58:59], v[74:75], off offset:1536
	ds_read_b128 v[74:77], v52 offset:1024
	s_waitcnt lgkmcnt(1)
	v_mul_f32_e32 v63, v41, v65
	v_fmac_f32_e32 v63, v40, v64
	v_mul_f32_e32 v64, v37, v67
	v_fmac_f32_e32 v64, v36, v66
	v_add_f32_e32 v63, v63, v64
	ds_read_b128 v[64:67], v52 offset:2048
	s_waitcnt lgkmcnt(1)
	v_mul_f32_e32 v73, v45, v75
	v_fmac_f32_e32 v73, v44, v74
	v_mul_f32_e32 v74, v43, v77
	v_fmac_f32_e32 v74, v42, v76
	v_add_f32_e32 v73, v73, v74
	ds_read_b128 v[74:77], v52 offset:3072
	s_waitcnt lgkmcnt(1)
	v_mul_f32_e32 v65, v47, v65
	v_fmac_f32_e32 v65, v46, v64
	v_mul_f32_e32 v64, v39, v67
	v_add_f32_e32 v63, 0, v63
	v_fmac_f32_e32 v64, v38, v66
	v_add_f32_e32 v63, v63, v73
	v_add_f32_e32 v64, v65, v64
	v_add_f32_e32 v63, v63, v64
	s_waitcnt lgkmcnt(0)
	v_mul_f32_e32 v64, v49, v75
	v_mul_f32_e32 v65, v35, v77
	v_fmac_f32_e32 v64, v48, v74
	v_fmac_f32_e32 v65, v34, v76
	v_add_f32_e32 v64, v64, v65
	v_add_f32_e32 v63, v63, v64
	ds_read_b128 v[64:67], v52 offset:4096
	ds_read_b128 v[74:77], v52 offset:5120
	s_nop 1
	v_mov_b32_dpp v73, v63 quad_perm:[1,0,3,2] row_mask:0xf bank_mask:0xf
	s_waitcnt lgkmcnt(1)
	v_mul_f32_e32 v65, v41, v65
	v_fmac_f32_e32 v65, v40, v64
	v_mul_f32_e32 v64, v37, v67
	v_fmac_f32_e32 v64, v36, v66
	v_add_f32_e32 v64, v65, v64
	s_waitcnt lgkmcnt(0)
	v_mul_f32_e32 v75, v45, v75
	v_add_f32_e32 v83, 0, v64
	v_fmac_f32_e32 v75, v44, v74
	v_mul_f32_e32 v74, v43, v77
	ds_read_b128 v[64:67], v52 offset:6144
	v_fmac_f32_e32 v74, v42, v76
	v_add_f32_e32 v74, v75, v74
	v_add_f32_e32 v83, v83, v74
	ds_read_b128 v[74:77], v52 offset:7168
	s_waitcnt lgkmcnt(1)
	v_mul_f32_e32 v65, v47, v65
	v_fmac_f32_e32 v65, v46, v64
	v_mul_f32_e32 v64, v39, v67
	v_fmac_f32_e32 v64, v38, v66
	v_add_f32_e32 v64, v65, v64
	s_waitcnt lgkmcnt(0)
	v_mul_f32_e32 v65, v49, v75
	v_mul_f32_e32 v66, v35, v77
	v_fmac_f32_e32 v65, v48, v74
	v_fmac_f32_e32 v66, v34, v76
	v_add_f32_e32 v64, v83, v64
	v_add_f32_e32 v65, v65, v66
	v_add_f32_e32 v64, v64, v65
	s_nop 1
	v_mov_b32_dpp v65, v64 quad_perm:[1,0,3,2] row_mask:0xf bank_mask:0xf
	v_add_f32_e32 v63, v63, v73
	s_nop 1
	v_mov_b32_dpp v66, v63 quad_perm:[2,3,0,1] row_mask:0xf bank_mask:0xf
	v_add_f32_e32 v64, v64, v65
	v_add_f32_e32 v63, v63, v66
	s_nop 1
	v_mov_b32_dpp v65, v64 quad_perm:[2,3,0,1] row_mask:0xf bank_mask:0xf
	s_nop 1
	v_mov_b32_dpp v66, v63 row_shl:4 row_mask:0xf bank_mask:0x5
	v_mov_b32_dpp v66, v63 row_shr:4 row_mask:0xf bank_mask:0xa
	v_add_f32_e32 v64, v64, v65
	v_add_f32_e32 v63, v63, v66
	s_nop 1
	v_mov_b32_dpp v65, v64 row_shl:4 row_mask:0xf bank_mask:0x5
	v_mov_b32_dpp v65, v64 row_shr:4 row_mask:0xf bank_mask:0xa
	s_nop 1
	v_mov_b32_dpp v66, v63 row_ror:8 row_mask:0xf bank_mask:0xf
	v_add_f32_e32 v64, v64, v65
	v_add_f32_e32 v63, v63, v66
	s_nop 1
	v_mov_b32_dpp v65, v64 row_ror:8 row_mask:0xf bank_mask:0xf
	v_mov_b32_e32 v66, v63
	v_mov_b32_e32 v120, v63
	s_nop 1
	v_permlane16_swap_b32_e32 v66, v120
	v_cndmask_b32_e64 v66, v120, v66, s[98:99]
	v_add_f32_e32 v65, v64, v65
	v_add_f32_e32 v63, v63, v66
	v_mov_b32_e32 v67, v65
	v_mov_b32_e32 v120, v65
	s_nop 1
	v_permlane16_swap_b32_e32 v67, v120
	v_cndmask_b32_e64 v67, v120, v67, s[98:99]
	ds_read_b128 v[74:77], v52 offset:8192
	ds_read_b128 v[78:81], v52 offset:9216
	v_add_f32_e32 v65, v65, v67
	s_waitcnt lgkmcnt(1)
; __device__ __forceinline__ float shx(float v, int o) { const int l = lane_now(); return __int_as_float(__builtin_amdgcn_ds_bpermute((l ^ o) << 2, __float_as_int(v))); }
; #define LAS __attribute__((address_space(3)))
; __device__ __forceinline__ float wave_sum(float v) {
; #pragma unroll
;     for (int o = 1; o < 64; o <<= 1) v += shx(v, o);
;     return v;
; template <int SRC, int EXTRA, bool OUT8 = false> ...
;     ...
;             for (int e = 0; e < 8; ++e) { float a = 0.f;
; #pragma unroll
;                 for (int j = 0; j < 4; ++j) { const f32x4 w = *(const LAS f32x4*)(w8s + e * 1024 + 256 * j + 4 * lane); a += (v[j].x * w.x + v[j].y * w.y) + (v[j].z * w.z + v[j].w * w.w); }
;                 d[e] = wave_sum(a); }
	v_mul_f32_e32 v67, v41, v75
	v_mul_f32_e32 v73, v37, v77
	v_fmac_f32_e32 v67, v40, v74
	v_fmac_f32_e32 v73, v36, v76
	ds_read_b128 v[74:77], v52 offset:10240
	v_add_f32_e32 v67, v67, v73
	s_waitcnt lgkmcnt(1)
	v_mul_f32_e32 v73, v45, v79
	v_fmac_f32_e32 v73, v44, v78
	v_mul_f32_e32 v78, v43, v81
	v_fmac_f32_e32 v78, v42, v80
	v_add_f32_e32 v67, 0, v67
	v_add_f32_e32 v73, v73, v78
	ds_read_b128 v[78:81], v52 offset:11264
	v_add_f32_e32 v67, v67, v73
	s_waitcnt lgkmcnt(1)
	v_mul_f32_e32 v73, v47, v75
	v_fmac_f32_e32 v73, v46, v74
	v_mul_f32_e32 v74, v39, v77
	v_fmac_f32_e32 v74, v38, v76
	v_add_f32_e32 v73, v73, v74
	v_add_f32_e32 v67, v67, v73
	s_waitcnt lgkmcnt(0)
	v_mul_f32_e32 v73, v49, v79
	v_mul_f32_e32 v74, v35, v81
	v_fmac_f32_e32 v73, v48, v78
	v_fmac_f32_e32 v74, v34, v80
	v_add_f32_e32 v73, v73, v74
	v_add_f32_e32 v67, v67, v73
	ds_read_b128 v[74:77], v52 offset:12288
	ds_read_b128 v[78:81], v52 offset:13312
	s_nop 1
	v_mov_b32_dpp v73, v67 quad_perm:[1,0,3,2] row_mask:0xf bank_mask:0xf
	s_waitcnt lgkmcnt(1)
	v_mul_f32_e32 v75, v41, v75
	v_fmac_f32_e32 v75, v40, v74
	v_mul_f32_e32 v74, v37, v77
	v_fmac_f32_e32 v74, v36, v76
	v_add_f32_e32 v74, v75, v74
	s_waitcnt lgkmcnt(0)
	v_mul_f32_e32 v79, v45, v79
	v_add_f32_e32 v87, 0, v74
	v_fmac_f32_e32 v79, v44, v78
	v_mul_f32_e32 v78, v43, v81
	ds_read_b128 v[74:77], v52 offset:14336
	v_fmac_f32_e32 v78, v42, v80
	v_add_f32_e32 v78, v79, v78
	v_add_f32_e32 v87, v87, v78
	ds_read_b128 v[78:81], v52 offset:15360
	s_waitcnt lgkmcnt(1)
	v_mul_f32_e32 v75, v47, v75
	v_fmac_f32_e32 v75, v46, v74
	v_mul_f32_e32 v74, v39, v77
	v_fmac_f32_e32 v74, v38, v76
	v_add_f32_e32 v74, v75, v74
	s_waitcnt lgkmcnt(0)
	v_mul_f32_e32 v75, v49, v79
	v_mul_f32_e32 v76, v35, v81
	v_fmac_f32_e32 v75, v48, v78
	v_fmac_f32_e32 v76, v34, v80
	v_add_f32_e32 v74, v87, v74
	v_add_f32_e32 v75, v75, v76
	v_add_f32_e32 v74, v74, v75
	v_add_f32_e32 v67, v67, v73
	s_nop 1
	v_mov_b32_dpp v75, v74 quad_perm:[1,0,3,2] row_mask:0xf bank_mask:0xf
	s_nop 1
	v_mov_b32_dpp v73, v67 quad_perm:[2,3,0,1] row_mask:0xf bank_mask:0xf
	v_add_f32_e32 v74, v74, v75
	s_nop 1
	v_mov_b32_dpp v75, v74 quad_perm:[2,3,0,1] row_mask:0xf bank_mask:0xf
	v_add_f32_e32 v67, v67, v73
	s_nop 1
	v_mov_b32_dpp v73, v67 row_shl:4 row_mask:0xf bank_mask:0x5
	v_mov_b32_dpp v73, v67 row_shr:4 row_mask:0xf bank_mask:0xa
	v_add_f32_e32 v74, v74, v75
	v_mov_b32_e32 v64, v63
	v_mov_b32_e32 v120, v63
	s_nop 1
	v_permlane32_swap_b32_e32 v64, v120
	v_cndmask_b32_e64 v64, v120, v64, s[100:101]
	s_nop 1
	v_mov_b32_dpp v75, v74 row_shl:4 row_mask:0xf bank_mask:0x5
	v_mov_b32_dpp v75, v74 row_shr:4 row_mask:0xf bank_mask:0xa
	v_add_f32_e32 v67, v67, v73
	s_nop 1
	v_mov_b32_dpp v73, v67 row_ror:8 row_mask:0xf bank_mask:0xf
	v_add_f32_e32 v74, v74, v75
	v_mov_b32_e32 v66, v65
	v_mov_b32_e32 v120, v65
	s_nop 1
	v_permlane32_swap_b32_e32 v66, v120
	v_cndmask_b32_e64 v66, v120, v66, s[100:101]
	s_nop 1
	v_mov_b32_dpp v75, v74 row_ror:8 row_mask:0xf bank_mask:0xf
	v_add_f32_e32 v67, v67, v73
	v_mov_b32_e32 v73, v67
	v_mov_b32_e32 v120, v67
	s_nop 1
	v_permlane16_swap_b32_e32 v73, v120
	v_cndmask_b32_e64 v73, v120, v73, s[98:99]
	v_add_f32_e32 v74, v74, v75
	v_add_f32_e32 v67, v67, v73
	v_mov_b32_e32 v75, v74
	v_mov_b32_e32 v120, v74
	s_nop 1
	v_permlane16_swap_b32_e32 v75, v120
	v_cndmask_b32_e64 v75, v120, v75, s[98:99]
	v_mov_b32_e32 v73, v67
	v_mov_b32_e32 v120, v67
	s_nop 1
	v_permlane32_swap_b32_e32 v73, v120
	v_cndmask_b32_e64 v73, v120, v73, s[100:101]
	v_add_f32_e32 v74, v74, v75
	ds_read_b128 v[76:79], v52 offset:16384
	ds_read_b128 v[80:83], v52 offset:17408
	v_mov_b32_e32 v75, v74
	v_mov_b32_e32 v120, v74
	s_nop 1
	v_permlane32_swap_b32_e32 v75, v120
	v_cndmask_b32_e64 v75, v120, v75, s[100:101]
	s_waitcnt lgkmcnt(1)
	v_mul_f32_e32 v77, v41, v77
	v_fmac_f32_e32 v77, v40, v76
	v_mul_f32_e32 v76, v37, v79
	v_fmac_f32_e32 v76, v36, v78
	v_add_f32_e32 v76, v77, v76
	s_waitcnt lgkmcnt(0)
	v_mul_f32_e32 v81, v45, v81
	v_add_f32_e32 v84, 0, v76
	v_fmac_f32_e32 v81, v44, v80
	v_mul_f32_e32 v80, v43, v83
	ds_read_b128 v[76:79], v52 offset:18432
	v_fmac_f32_e32 v80, v42, v82
	v_add_f32_e32 v80, v81, v80
	v_add_f32_e32 v84, v84, v80
	ds_read_b128 v[80:83], v52 offset:19456
	s_waitcnt lgkmcnt(1)
	v_mul_f32_e32 v77, v47, v77
	v_fmac_f32_e32 v77, v46, v76
	v_mul_f32_e32 v76, v39, v79
	v_fmac_f32_e32 v76, v38, v78
	v_add_f32_e32 v76, v77, v76
	s_waitcnt lgkmcnt(0)
	v_mul_f32_e32 v77, v49, v81
	v_mul_f32_e32 v78, v35, v83
	v_fmac_f32_e32 v77, v48, v80
	v_fmac_f32_e32 v78, v34, v82
	v_add_f32_e32 v76, v84, v76
	v_add_f32_e32 v77, v77, v78
	v_add_f32_e32 v84, v76, v77
	ds_read_b128 v[76:79], v52 offset:20480
	s_nop 1
	v_mov_b32_dpp v90, v84 quad_perm:[1,0,3,2] row_mask:0xf bank_mask:0xf
	ds_read_b128 v[80:83], v52 offset:21504
	s_waitcnt lgkmcnt(1)
	v_mul_f32_e32 v77, v41, v77
	v_fmac_f32_e32 v77, v40, v76
	v_mul_f32_e32 v76, v37, v79
	v_fmac_f32_e32 v76, v36, v78
	v_add_f32_e32 v76, v77, v76
	s_waitcnt lgkmcnt(0)
	v_mul_f32_e32 v81, v45, v81
	v_add_f32_e32 v91, 0, v76
	v_fmac_f32_e32 v81, v44, v80
	v_mul_f32_e32 v80, v43, v83
	ds_read_b128 v[76:79], v52 offset:22528
	v_fmac_f32_e32 v80, v42, v82
	v_add_f32_e32 v80, v81, v80
	v_add_f32_e32 v91, v91, v80
	ds_read_b128 v[80:83], v52 offset:23552
	s_waitcnt lgkmcnt(1)
	v_mul_f32_e32 v77, v47, v77
	v_fmac_f32_e32 v77, v46, v76
	v_mul_f32_e32 v76, v39, v79
	v_fmac_f32_e32 v76, v38, v78
	v_add_f32_e32 v76, v77, v76
	s_waitcnt lgkmcnt(0)
; __device__ __forceinline__ float shx(float v, int o) { const int l = lane_now(); return __int_as_float(__builtin_amdgcn_ds_bpermute((l ^ o) << 2, __float_as_int(v))); }
; #define LAS __attribute__((address_space(3)))
; __device__ __forceinline__ float wave_sum(float v) {
; #pragma unroll
;     for (int o = 1; o < 64; o <<= 1) v += shx(v, o);
;     return v;
; template <int SRC, int EXTRA, bool OUT8 = false> ...
;     ...
;             for (int e = 0; e < 8; ++e) { float a = 0.f;
; #pragma unroll
;                 for (int j = 0; j < 4; ++j) { const f32x4 w = *(const LAS f32x4*)(w8s + e * 1024 + 256 * j + 4 * lane); a += (v[j].x * w.x + v[j].y * w.y) + (v[j].z * w.z + v[j].w * w.w); }
;                 d[e] = wave_sum(a); }
	v_mul_f32_e32 v77, v49, v81
	v_mul_f32_e32 v78, v35, v83
	v_fmac_f32_e32 v77, v48, v80
	v_fmac_f32_e32 v78, v34, v82
	v_add_f32_e32 v76, v91, v76
	v_add_f32_e32 v77, v77, v78
	v_add_f32_e32 v76, v76, v77
	s_nop 1
	v_mov_b32_dpp v77, v76 quad_perm:[1,0,3,2] row_mask:0xf bank_mask:0xf
	v_add_f32_e32 v78, v84, v90
	s_nop 1
	v_mov_b32_dpp v79, v78 quad_perm:[2,3,0,1] row_mask:0xf bank_mask:0xf
	v_add_f32_e32 v76, v76, v77
	v_add_f32_e32 v78, v78, v79
	s_nop 1
	v_mov_b32_dpp v77, v76 quad_perm:[2,3,0,1] row_mask:0xf bank_mask:0xf
	s_nop 1
	v_mov_b32_dpp v79, v78 row_shl:4 row_mask:0xf bank_mask:0x5
	v_mov_b32_dpp v79, v78 row_shr:4 row_mask:0xf bank_mask:0xa
	v_add_f32_e32 v76, v76, v77
	v_add_f32_e32 v78, v78, v79
	s_nop 1
	v_mov_b32_dpp v77, v76 row_shl:4 row_mask:0xf bank_mask:0x5
	v_mov_b32_dpp v77, v76 row_shr:4 row_mask:0xf bank_mask:0xa
	s_nop 1
	v_mov_b32_dpp v79, v78 row_ror:8 row_mask:0xf bank_mask:0xf
	v_add_f32_e32 v76, v76, v77
	v_add_f32_e32 v78, v78, v79
	s_nop 1
	v_mov_b32_dpp v77, v76 row_ror:8 row_mask:0xf bank_mask:0xf
	v_mov_b32_e32 v79, v78
	v_mov_b32_e32 v120, v78
	s_nop 1
	v_permlane16_swap_b32_e32 v79, v120
	v_cndmask_b32_e64 v79, v120, v79, s[98:99]
	v_add_f32_e32 v80, v76, v77
	v_mov_b32_e32 v81, v80
	v_mov_b32_e32 v120, v80
	s_nop 1
	v_permlane16_swap_b32_e32 v81, v120
	v_cndmask_b32_e64 v81, v120, v81, s[98:99]
	v_add_f32_e32 v76, v78, v79
	ds_read_b128 v[84:87], v52 offset:25600
	v_add_f32_e32 v78, v80, v81
	ds_read_b128 v[80:83], v52 offset:24576
	s_waitcnt lgkmcnt(1)
	v_mul_f32_e32 v85, v45, v85
	v_fmac_f32_e32 v85, v44, v84
	v_mul_f32_e32 v84, v43, v87
	s_waitcnt lgkmcnt(0)
	v_mul_f32_e32 v81, v41, v81
	v_fmac_f32_e32 v81, v40, v80
	v_mul_f32_e32 v80, v37, v83
	v_fmac_f32_e32 v80, v36, v82
	v_add_f32_e32 v80, v81, v80
	v_add_f32_e32 v88, 0, v80
	ds_read_b128 v[80:83], v52 offset:26624
	v_fmac_f32_e32 v84, v42, v86
	v_add_f32_e32 v84, v85, v84
	v_add_f32_e32 v88, v88, v84
	ds_read_b128 v[84:87], v52 offset:27648
	s_waitcnt lgkmcnt(1)
	v_mul_f32_e32 v81, v47, v81
	v_fmac_f32_e32 v81, v46, v80
	v_mul_f32_e32 v80, v39, v83
	v_fmac_f32_e32 v80, v38, v82
	v_add_f32_e32 v80, v81, v80
	s_waitcnt lgkmcnt(0)
	v_mul_f32_e32 v81, v49, v85
	v_mul_f32_e32 v82, v35, v87
	v_fmac_f32_e32 v81, v48, v84
	v_fmac_f32_e32 v82, v34, v86
	v_add_f32_e32 v80, v88, v80
	v_add_f32_e32 v81, v81, v82
	v_add_f32_e32 v88, v80, v81
	v_mbcnt_lo_u32_b32 v89, -1, 0
	v_mbcnt_hi_u32_b32 v89, -1, v89
	v_mbcnt_lo_u32_b32 v90, -1, 0
	v_mbcnt_hi_u32_b32 v90, -1, v90
	v_mbcnt_lo_u32_b32 v91, -1, 0
	v_mbcnt_hi_u32_b32 v91, -1, v91
	v_mbcnt_lo_u32_b32 v92, -1, 0
	v_mbcnt_hi_u32_b32 v92, -1, v92
	v_mbcnt_lo_u32_b32 v93, -1, 0
	v_mbcnt_hi_u32_b32 v93, -1, v93
	ds_read_b128 v[80:83], v52 offset:28672
	s_nop 1
	v_mov_b32_dpp v94, v88 quad_perm:[1,0,3,2] row_mask:0xf bank_mask:0xf
	ds_read_b128 v[84:87], v52 offset:29696
	s_waitcnt lgkmcnt(1)
	v_mul_f32_e32 v41, v41, v81
	v_mul_f32_e32 v37, v37, v83
	v_fmac_f32_e32 v41, v40, v80
	v_fmac_f32_e32 v37, v36, v82
	ds_read_b128 v[80:83], v52 offset:30720
	v_add_f32_e32 v36, v41, v37
	s_waitcnt lgkmcnt(1)
	v_mul_f32_e32 v37, v45, v85
	v_mul_f32_e32 v40, v43, v87
	v_fmac_f32_e32 v37, v44, v84
	v_fmac_f32_e32 v40, v42, v86
	v_add_f32_e32 v37, v37, v40
	ds_read_b128 v[40:43], v52 offset:31744
	v_add_f32_e32 v36, 0, v36
	v_add_f32_e32 v36, v36, v37
	s_waitcnt lgkmcnt(1)
	v_mul_f32_e32 v37, v47, v81
	v_mul_f32_e32 v39, v39, v83
	v_fmac_f32_e32 v37, v46, v80
	v_fmac_f32_e32 v39, v38, v82
	v_add_f32_e32 v37, v37, v39
	v_add_f32_e32 v36, v36, v37
	s_waitcnt lgkmcnt(0)
	v_mul_f32_e32 v37, v49, v41
	v_mul_f32_e32 v35, v35, v43
	v_fmac_f32_e32 v37, v48, v40
	v_fmac_f32_e32 v35, v34, v42
	v_add_f32_e32 v34, v37, v35
	v_add_f32_e32 v34, v36, v34
	s_nop 1
	v_mov_b32_dpp v35, v34 quad_perm:[1,0,3,2] row_mask:0xf bank_mask:0xf
	v_add_f32_e32 v36, v88, v94
	s_nop 1
	v_mov_b32_dpp v37, v36 quad_perm:[2,3,0,1] row_mask:0xf bank_mask:0xf
	v_add_f32_e32 v34, v34, v35
	s_nop 1
	v_mov_b32_dpp v35, v34 quad_perm:[2,3,0,1] row_mask:0xf bank_mask:0xf
	v_add_f32_e32 v36, v36, v37
	s_nop 1
	v_mov_b32_dpp v37, v36 row_shl:4 row_mask:0xf bank_mask:0x5
	v_mov_b32_dpp v37, v36 row_shr:4 row_mask:0xf bank_mask:0xa
	v_add_f32_e32 v34, v34, v35
	v_mov_b32_e32 v77, v76
	v_mov_b32_e32 v120, v76
	s_nop 1
	v_permlane32_swap_b32_e32 v77, v120
	v_cndmask_b32_e64 v77, v120, v77, s[100:101]
	s_nop 1
	v_mov_b32_dpp v35, v34 row_shl:4 row_mask:0xf bank_mask:0x5
	v_mov_b32_dpp v35, v34 row_shr:4 row_mask:0xf bank_mask:0xa
	v_add_f32_e32 v36, v36, v37
	s_nop 1
	v_mov_b32_dpp v37, v36 row_ror:8 row_mask:0xf bank_mask:0xf
	v_add_f32_e32 v34, v34, v35
	v_mov_b32_e32 v79, v78
	v_mov_b32_e32 v120, v78
	s_nop 1
	v_permlane32_swap_b32_e32 v79, v120
	v_cndmask_b32_e64 v79, v120, v79, s[100:101]
	s_nop 1
	v_mov_b32_dpp v35, v34 row_ror:8 row_mask:0xf bank_mask:0xf
	v_add_f32_e32 v36, v36, v37
	v_mov_b32_e32 v37, v36
	v_mov_b32_e32 v120, v36
	s_nop 1
	v_permlane16_swap_b32_e32 v37, v120
	v_cndmask_b32_e64 v37, v120, v37, s[98:99]
	v_add_f32_e32 v38, v34, v35
	v_mov_b32_e32 v39, v38
	v_mov_b32_e32 v120, v38
	s_nop 1
	v_permlane16_swap_b32_e32 v39, v120
	v_cndmask_b32_e64 v39, v120, v39, s[98:99]
	v_add_f32_e32 v34, v36, v37
	v_add_f32_e32 v36, v38, v39
	v_mov_b32_e32 v35, v34
	v_mov_b32_e32 v120, v34
	s_nop 1
	v_permlane32_swap_b32_e32 v35, v120
	v_cndmask_b32_e64 v35, v120, v35, s[100:101]
	v_mov_b32_e32 v37, v36
	v_mov_b32_e32 v120, v36
	s_nop 1
	v_permlane32_swap_b32_e32 v37, v120
	v_cndmask_b32_e64 v37, v120, v37, s[100:101]
	s_and_saveexec_b64 s[22:23], s[6:7]
	s_cbranch_execz .LBB0_58
; template <int SRC, int EXTRA, bool OUT8 = false> ...
;     ...
;             if (EXTRA == 1) {
;                 float x = d[0];
; #pragma unroll
;                 for (int e = 1; e < 8; ++e) x = (lane == e) ? d[e] : x;
;                 if (lane < 8) { x += bf8[lane]; const float ls = (x >= 0.f) ? -log1pf(__expf(-x)) : (x - log1pf(__expf(x))); logf[(size_t)lane * M + row] = ls; }
	global_load_dword v38, v[54:55], off
	v_add_f32_e32 v41, v65, v66
	v_add_f32_e32 v42, v63, v64
	v_add_f32_e32 v40, v67, v73
	v_cndmask_b32_e64 v41, v42, v41, s[20:21]
	v_add_f32_e32 v39, v74, v75
	v_cndmask_b32_e64 v40, v41, v40, s[18:19]
	v_add_f32_e32 v36, v36, v37
	v_add_f32_e32 v37, v76, v77
	v_cndmask_b32_e64 v39, v40, v39, s[16:17]
	v_add_f32_e32 v34, v34, v35
	v_add_f32_e32 v35, v78, v79
	v_cndmask_b32_e64 v37, v39, v37, s[14:15]
	v_cndmask_b32_e64 v35, v37, v35, s[12:13]
	v_cndmask_b32_e64 v34, v35, v34, s[10:11]
	v_cndmask_b32_e64 v34, v34, v36, s[8:9]
	s_waitcnt vmcnt(0)
	v_add_f32_e32 v34, v34, v38
	v_cmp_le_f32_e32 vcc, 0, v34
	s_and_saveexec_b64 s[42:43], vcc
	s_xor_b64 s[42:43], exec, s[42:43]
	s_cbranch_execz .LBB0_64
	v_mul_f32_e32 v34, 0xbfb8aa3b, v34
	v_exp_f32_e32 v48, v34
	s_nop 0
	v_add_f32_e32 v36, 1.0, v48
	v_frexp_mant_f32_e32 v38, v36
	v_cvt_f64_f32_e32 v[34:35], v36
	v_frexp_exp_i32_f64_e32 v34, v[34:35]
	v_cmp_gt_f32_e32 vcc, s47, v38
	v_add_f32_e32 v37, -1.0, v36
	v_sub_f32_e32 v39, v37, v36
	v_subbrev_co_u32_e32 v42, vcc, 0, v34, vcc
	v_sub_u32_e32 v34, 0, v42
	v_sub_f32_e32 v37, v48, v37
	v_add_f32_e32 v39, 1.0, v39
	v_ldexp_f32 v35, v36, v34
	v_add_f32_e32 v37, v37, v39
	v_add_f32_e32 v36, -1.0, v35
	v_add_f32_e32 v38, 1.0, v35
	v_ldexp_f32 v34, v37, v34
	v_add_f32_e32 v37, 1.0, v36
	v_add_f32_e32 v39, -1.0, v38
	v_sub_f32_e32 v37, v35, v37
	v_sub_f32_e32 v35, v35, v39
	v_add_f32_e32 v37, v34, v37
	v_add_f32_e32 v34, v34, v35
	v_add_f32_e32 v43, v38, v34
	v_rcp_f32_e32 v45, v43
	v_sub_f32_e32 v35, v43, v38
	v_sub_f32_e32 v44, v34, v35
	v_add_f32_e32 v35, v36, v37
	v_mul_f32_e32 v47, v35, v45
	v_sub_f32_e32 v34, v35, v36
	v_mul_f32_e32 v36, v43, v47
	v_fma_f32 v38, v47, v43, -v36
	v_fmac_f32_e32 v38, v47, v44
	v_sub_f32_e32 v46, v37, v34
	v_add_f32_e32 v34, v36, v38
	v_sub_f32_e32 v37, v35, v34
	v_pk_add_f32 v[40:41], v[34:35], v[36:37] neg_lo:[0,1] neg_hi:[0,1]
	v_mov_b32_e32 v39, v34
	v_pk_add_f32 v[34:35], v[40:41], v[38:39] neg_lo:[0,1] neg_hi:[0,1]
	v_cmp_neq_f32_e32 vcc, s49, v48
	v_add_f32_e32 v35, v46, v35
	v_add_f32_e32 v34, v34, v35
	v_add_f32_e32 v35, v37, v34
	v_mul_f32_e32 v46, v45, v35
	v_mul_f32_e32 v36, v43, v46
	v_fma_f32 v38, v46, v43, -v36
	v_fmac_f32_e32 v38, v46, v44
	v_sub_f32_e32 v37, v37, v35
	v_add_f32_e32 v43, v34, v37
	v_add_f32_e32 v34, v36, v38
	v_sub_f32_e32 v37, v35, v34
	v_pk_add_f32 v[40:41], v[34:35], v[36:37] neg_lo:[0,1] neg_hi:[0,1]
	v_mov_b32_e32 v39, v34
	v_pk_add_f32 v[34:35], v[40:41], v[38:39] neg_lo:[0,1] neg_hi:[0,1]
	s_nop 0
	v_add_f32_e32 v35, v43, v35
	v_add_f32_e32 v34, v34, v35
	v_add_f32_e32 v35, v47, v46
	v_add_f32_e32 v34, v37, v34
	v_sub_f32_e32 v36, v35, v47
	v_mul_f32_e32 v34, v45, v34
	v_sub_f32_e32 v36, v46, v36
	v_add_f32_e32 v36, v36, v34
	v_add_f32_e32 v38, v35, v36
	v_mul_f32_e32 v39, v38, v38
	v_fmamk_f32 v34, v39, 0x3e9b6dac, v69
	v_fmaak_f32 v63, v39, v34, 0x3f2aaada
	v_cvt_f32_i32_e32 v34, v42
	v_sub_f32_e32 v35, v38, v35
	v_sub_f32_e32 v35, v36, v35
	v_ldexp_f32 v40, v35, 1
	v_mul_f32_e32 v35, v38, v39
	v_ldexp_f32 v37, v38, 1
	v_pk_mul_f32 v[38:39], v[34:35], v[62:63]
	s_nop 0
	v_fma_f32 v36, v34, s48, -v38
	v_fmac_f32_e32 v36, 0xb102e308, v34
	v_pk_add_f32 v[34:35], v[38:39], v[36:37]
	s_nop 0
	v_sub_f32_e32 v37, v35, v37
	v_sub_f32_e32 v37, v39, v37
	v_add_f32_e32 v41, v40, v37
	v_mov_b32_e32 v40, v38
	v_pk_add_f32 v[38:39], v[34:35], v[38:39] neg_lo:[0,1] neg_hi:[0,1]
	v_pk_add_f32 v[42:43], v[34:35], v[40:41]
	v_mov_b32_e32 v37, v34
	v_mov_b32_e32 v39, v43
	v_pk_add_f32 v[44:45], v[36:37], v[38:39] neg_lo:[0,1] neg_hi:[0,1]
	v_pk_add_f32 v[36:37], v[36:37], v[38:39]
	v_mov_b32_e32 v40, v41
	v_pk_add_f32 v[38:39], v[36:37], v[34:35] op_sel:[1,0] op_sel_hi:[0,1] neg_lo:[0,1] neg_hi:[0,1]
	v_pk_add_f32 v[46:47], v[42:43], v[38:39] op_sel_hi:[1,0] neg_lo:[0,1] neg_hi:[0,1]
	v_mov_b32_e32 v42, v43
	v_mov_b32_e32 v43, v37
	v_pk_mov_b32 v[38:39], v[34:35], v[38:39] op_sel:[1,0]
	v_mov_b32_e32 v41, v34
	v_pk_add_f32 v[38:39], v[42:43], v[38:39] neg_lo:[0,1] neg_hi:[0,1]
	v_mov_b32_e32 v46, v44
	v_pk_add_f32 v[34:35], v[40:41], v[38:39] neg_lo:[0,1] neg_hi:[0,1]
	v_mov_b32_e32 v45, v37
	v_pk_add_f32 v[38:39], v[46:47], v[34:35]
	s_nop 0
	v_pk_add_f32 v[40:41], v[38:39], v[38:39] op_sel:[0,1] op_sel_hi:[1,0]
	s_nop 0
	v_pk_add_f32 v[36:37], v[36:37], v[40:41] op_sel:[1,0] op_sel_hi:[0,1]
	v_mov_b32_e32 v39, v36
	v_pk_add_f32 v[42:43], v[38:39], v[44:45] neg_lo:[0,1] neg_hi:[0,1]
	v_mov_b32_e32 v35, v40
	v_sub_f32_e32 v37, v38, v42
	v_pk_add_f32 v[34:35], v[34:35], v[42:43] neg_lo:[0,1] neg_hi:[0,1]
	v_sub_f32_e32 v37, v44, v37
	v_add_f32_e32 v34, v34, v37
	v_add_f32_e32 v34, v34, v35
	v_add_f32_e32 v34, v36, v34
	v_cndmask_b32_e32 v34, v70, v34, vcc
	v_cmp_ngt_f32_e32 vcc, -1.0, v48
	s_nop 1
	v_cndmask_b32_e32 v34, v71, v34, vcc
	v_cmp_neq_f32_e32 vcc, -1.0, v48
	s_nop 1
	v_cndmask_b32_e32 v34, v72, v34, vcc
	v_cmp_lt_f32_e64 vcc, |v48|, s50
	s_nop 1
	v_cndmask_b32_e32 v34, v34, v48, vcc
	v_xor_b32_e32 v35, 0x80000000, v34

; __device__ __forceinline__ float shx(float v, int o) { const int l = lane_now(); return __int_as_float(__builtin_amdgcn_ds_bpermute((l ^ o) << 2, __float_as_int(v))); }
; __device__ __forceinline__ float wave_sum(float v) {
; #pragma unroll
;     for (int o = 1; o < 64; o <<= 1) v += shx(v, o);
;     return v;
; template <int SRC, int EXTRA, bool OUT8 = false> ...
;     ...
;         float s = 0.f;
; #pragma unroll
;         for (int j = 0; j < 4; ++j) s += (v[j].x + v[j].y) + (v[j].z + v[j].w);
;         const float mean = wave_sum(s) * (1.f / 1024.f); float s2 = 0.f;
; #pragma unroll
;         for (int j = 0; j < 4; ++j) { v[j] = v[j] - mean; s2 += (v[j].x * v[j].x + v[j].y * v[j].y) + (v[j].z * v[j].z + v[j].w * v[j].w); }
;         const float rstd = 1.f / sqrtf(wave_sum(s2) * (1.f / 1024.f) + LN_EPS);
;         if (stats && lane == 0) { stats[2 * row] = mean; stats[2 * row + 1] = rstd; }
.LBB0_1057:
	global_load_dwordx4 v[44:47], v[58:59], off offset:-3072
	global_load_dwordx4 v[40:43], v[58:59], off offset:-2048
	global_load_dwordx4 v[36:39], v[58:59], off offset:-1024
	s_waitcnt lgkmcnt(0)
	global_load_dwordx4 v[32:35], v[58:59], off
	s_waitcnt vmcnt(3)
	v_mov_b32_e32 v62, v45
	v_mov_b32_e32 v63, v46
	v_mov_b32_e32 v64, v44
	v_mov_b32_e32 v65, v47
	s_waitcnt vmcnt(2)
	v_mov_b32_e32 v72, v41
	v_mov_b32_e32 v73, v42
	v_mov_b32_e32 v74, v40
	v_mov_b32_e32 v75, v43
	v_pk_add_f32 v[62:63], v[62:63], v[64:65]
	v_pk_add_f32 v[64:65], v[72:73], v[74:75]
	v_add_f32_e32 v61, v62, v63
	v_pk_add_f32 v[62:63], v[64:65], v[64:65] op_sel:[0,1] op_sel_hi:[1,0]
	s_waitcnt vmcnt(1)
	v_add_f32_e32 v76, v36, v37
	v_add_f32_e32 v78, v38, v39
	s_waitcnt vmcnt(0)
	v_mov_b32_e32 v81, v32
	v_mov_b32_e32 v77, v34
	v_mov_b32_e32 v79, v35
	v_add_f32_e32 v80, 0, v61
	v_mov_b32_e32 v63, v33
	v_pk_add_f32 v[72:73], v[76:77], v[78:79]
	v_pk_add_f32 v[62:63], v[80:81], v[62:63]
	v_pk_add_f32 v[62:63], v[62:63], v[72:73]
	v_add_f32_e32 v61, v62, v63
	s_nop 1
	v_mov_b32_dpp v50, v61 quad_perm:[1,0,3,2] row_mask:0xf bank_mask:0xf
	v_add_f32_e32 v50, v61, v50
	s_nop 1
	v_mov_b32_dpp v61, v50 quad_perm:[2,3,0,1] row_mask:0xf bank_mask:0xf
	v_add_f32_e32 v50, v50, v61
	s_nop 1
	v_mov_b32_dpp v61, v50 row_shl:4 row_mask:0xf bank_mask:0x5
	v_mov_b32_dpp v61, v50 row_shr:4 row_mask:0xf bank_mask:0xa
	v_add_f32_e32 v50, v50, v61
	s_nop 1
	v_mov_b32_dpp v61, v50 row_ror:8 row_mask:0xf bank_mask:0xf
	v_add_f32_e32 v50, v50, v61
	v_mov_b32_e32 v61, v50
	v_mov_b32_e32 v120, v50
	s_nop 1
	v_permlane16_swap_b32_e32 v61, v120
	v_cndmask_b32_e64 v61, v120, v61, s[98:99]
	v_add_f32_e32 v50, v50, v61
	v_mov_b32_e32 v61, v50
	v_mov_b32_e32 v120, v50
	s_nop 1
	v_permlane32_swap_b32_e32 v61, v120
	v_cndmask_b32_e64 v61, v120, v61, s[100:101]
	v_add_f32_e32 v61, v50, v61
	v_fmamk_f32 v65, v61, 0xba800000, v47
	v_fmamk_f32 v45, v61, 0xba800000, v45
	v_fmamk_f32 v43, v61, 0xba800000, v43
	v_fmamk_f32 v41, v61, 0xba800000, v41
	v_fmamk_f32 v64, v61, 0xba800000, v46
	v_fmac_f32_e32 v44, 0xba800000, v61
	v_fmamk_f32 v42, v61, 0xba800000, v42
	v_fmac_f32_e32 v40, 0xba800000, v61
	v_fmamk_f32 v63, v61, 0xba800000, v39
	v_fmamk_f32 v62, v61, 0xba800000, v38
	v_fmamk_f32 v37, v61, 0xba800000, v37
	v_fmamk_f32 v47, v61, 0xba800000, v35
	v_fmamk_f32 v46, v61, 0xba800000, v34
	v_mul_f32_e32 v34, v45, v45
	v_mul_f32_e32 v35, v65, v65
	v_mul_f32_e32 v38, v41, v41
	v_mul_f32_e32 v39, v43, v43
	v_fmac_f32_e32 v36, 0xba800000, v61
	v_fmamk_f32 v33, v61, 0xba800000, v33
	v_mul_f32_e32 v50, v37, v37
	v_mul_f32_e32 v72, v63, v63
	v_fmac_f32_e32 v34, v44, v44
	v_fmac_f32_e32 v35, v64, v64
	v_fmac_f32_e32 v38, v40, v40
	v_fmac_f32_e32 v39, v42, v42
	v_fmac_f32_e32 v32, 0xba800000, v61
	v_mul_f32_e32 v73, v33, v33
	v_mul_f32_e32 v74, v47, v47
	v_fmac_f32_e32 v50, v36, v36
	v_fmac_f32_e32 v72, v62, v62
	v_add_f32_e32 v34, v34, v35
	v_add_f32_e32 v35, v38, v39
	v_fmac_f32_e32 v73, v32, v32
	v_fmac_f32_e32 v74, v46, v46
	v_add_f32_e32 v38, v50, v72
	v_add_f32_e32 v34, v34, v35
	v_add_f32_e32 v39, v73, v74
	v_add_f32_e32 v34, v38, v34
	v_add_f32_e32 v34, v39, v34
	s_nop 1
	v_mov_b32_dpp v35, v34 quad_perm:[1,0,3,2] row_mask:0xf bank_mask:0xf
	v_add_f32_e32 v34, v34, v35
	s_nop 1
	v_mov_b32_dpp v35, v34 quad_perm:[2,3,0,1] row_mask:0xf bank_mask:0xf
	v_add_f32_e32 v34, v34, v35
	s_nop 1
	v_mov_b32_dpp v35, v34 row_shl:4 row_mask:0xf bank_mask:0x5
	v_mov_b32_dpp v35, v34 row_shr:4 row_mask:0xf bank_mask:0xa
	v_add_f32_e32 v34, v34, v35
	s_nop 1
	v_mov_b32_dpp v35, v34 row_ror:8 row_mask:0xf bank_mask:0xf
	v_add_f32_e32 v34, v34, v35
	v_mov_b32_e32 v35, v34
	v_mov_b32_e32 v120, v34
	s_nop 1
	v_permlane16_swap_b32_e32 v35, v120
	v_cndmask_b32_e64 v35, v120, v35, s[98:99]
	v_add_f32_e32 v34, v34, v35
	v_mov_b32_e32 v35, v34
	v_mov_b32_e32 v120, v34
	s_nop 1
	v_permlane32_swap_b32_e32 v35, v120
	v_cndmask_b32_e64 v35, v120, v35, s[100:101]
	v_add_f32_e32 v34, v34, v35
	v_fmamk_f32 v34, v34, 0x3a800000, v49
	v_mul_f32_e32 v35, 0x4f800000, v34
	v_cmp_gt_f32_e32 vcc, s31, v34
	s_nop 1
	v_cndmask_b32_e32 v34, v34, v35, vcc
	v_sqrt_f32_e32 v35, v34
	s_nop 0
	v_add_u32_e32 v38, -1, v35
	v_add_u32_e32 v39, 1, v35
	v_fma_f32 v50, -v38, v35, v34
	v_fma_f32 v71, -v39, v35, v34
	v_cmp_ge_f32_e64 s[28:29], 0, v50
	s_nop 1
	v_cndmask_b32_e64 v35, v35, v38, s[28:29]
	v_cmp_lt_f32_e64 s[28:29], 0, v71
	s_nop 1
	v_cndmask_b32_e64 v35, v35, v39, s[28:29]
	v_mul_f32_e32 v38, 0x37800000, v35
	v_cndmask_b32_e32 v35, v35, v38, vcc
	v_cmp_class_f32_e32 vcc, v34, v66
	s_nop 1
	v_cndmask_b32_e32 v34, v35, v34, vcc
	v_div_scale_f32 v35, s[28:29], v34, v34, 1.0
	v_rcp_f32_e32 v38, v35
	v_div_scale_f32 v39, vcc, 1.0, v34, 1.0
	v_fma_f32 v50, -v35, v38, 1.0
	v_fmac_f32_e32 v38, v50, v38
	v_mul_f32_e32 v50, v39, v38
	v_fma_f32 v71, -v35, v50, v39
	v_fmac_f32_e32 v50, v71, v38
	v_fma_f32 v35, -v35, v50, v39
	v_div_fmas_f32 v35, v35, v38, v50
	v_div_fixup_f32 v50, v35, v34, 1.0
	s_and_saveexec_b64 s[28:29], s[10:11]
	s_cbranch_execz .LBB0_1059
	s_ashr_i32 s45, s44, 31
	s_lshl_b64 s[52:53], s[44:45], 2
	s_add_u32 s52, s3, s52
	v_mul_f32_e32 v34, 0x3a800000, v61
	s_addc_u32 s53, s40, s53
	v_mov_b32_e32 v35, v50
	global_store_dwordx2 v51, v[34:35], s[52:53]
; #define LAS __attribute__((address_space(3)))
; __device__ __forceinline__ unsigned pk2(float lo, float hi) { return f2bf(lo) | (f2bf(hi) << 16); }
; template <int SRC, int EXTRA, bool OUT8 = false> ...
;     ...
;         if (stats && lane == 0) { stats[2 * row] = mean; stats[2 * row + 1] = rstd; }
; #pragma unroll
;         for (int j = 0; j < 4; ++j) { v[j] = v[j] * rstd * gv[j] + bv[j]; if (of32) *(f32x4*)(of32 + (size_t)row * 1024 + 256 * j + 4 * lane) = v[j];
;             if (obf) { if constexpr (OUT8) { int w = 0; w = __builtin_amdgcn_cvt_pk_fp8_f32(v[j].x, v[j].y, w, false); w = __builtin_amdgcn_cvt_pk_fp8_f32(v[j].z, v[j].w, w, true); *(unsigned*)((unsigned char*)obf + (size_t)row * 1024 + 256 * j + 4 * lane) = (unsigned)w; }
;                 else { v2u o; o.x = pk2(v[j].x, v[j].y); o.y = pk2(v[j].z, v[j].w); *(v2u*)(obf + (size_t)row * 1024 + 256 * j + 4 * lane) = o; } } }
;         if (EXTRA != 0) {
;             float d[8];
; #pragma unroll
;             for (int e = 0; e < 8; ++e) { float a = 0.f;
; #pragma unroll
;                 for (int j = 0; j < 4; ++j) { const f32x4 w = *(const LAS f32x4*)(w8s + e * 1024 + 256 * j + 4 * lane); a += (v[j].x * w.x + v[j].y * w.y) + (v[j].z * w.z + v[j].w * w.w); }
;                 d[e] = wave_sum(a); }
.LBB0_1059:
	s_or_b64 exec, exec, s[28:29]
	v_pk_mul_f32 v[38:39], v[44:45], v[50:51] op_sel_hi:[1,0]
	v_pk_mul_f32 v[34:35], v[64:65], v[50:51] op_sel_hi:[1,0]
	v_pk_fma_f32 v[38:39], v[0:1], v[38:39], v[8:9]
	v_pk_fma_f32 v[34:35], v[2:3], v[34:35], v[10:11]
	v_bfe_u32 v44, v38, 16, 1
	v_add3_u32 v44, v38, v44, s35
	v_bfe_u32 v45, v39, 16, 1
	v_lshrrev_b32_e32 v44, 16, v44
	v_add3_u32 v45, v39, v45, s35
	v_and_or_b32 v44, v45, s42, v44
	v_bfe_u32 v45, v34, 16, 1
	v_add3_u32 v45, v34, v45, s35
	v_bfe_u32 v61, v35, 16, 1
	v_lshrrev_b32_e32 v45, 16, v45
	v_add3_u32 v61, v35, v61, s35
	v_and_or_b32 v45, v61, s42, v45
	global_store_dwordx2 v[56:57], v[44:45], off offset:-1536
	v_pk_mul_f32 v[42:43], v[42:43], v[50:51] op_sel_hi:[1,0]
	v_pk_mul_f32 v[44:45], v[40:41], v[50:51] op_sel_hi:[1,0]
	v_pk_fma_f32 v[40:41], v[6:7], v[42:43], v[14:15]
	v_pk_fma_f32 v[42:43], v[4:5], v[44:45], v[12:13]
	v_bfe_u32 v61, v41, 16, 1
	v_bfe_u32 v44, v42, 16, 1
	v_add3_u32 v44, v42, v44, s35
	v_bfe_u32 v45, v43, 16, 1
	v_lshrrev_b32_e32 v44, 16, v44
	v_add3_u32 v45, v43, v45, s35
	v_and_or_b32 v44, v45, s42, v44
	v_bfe_u32 v45, v40, 16, 1
	v_add3_u32 v45, v40, v45, s35
	v_lshrrev_b32_e32 v45, 16, v45
	v_add3_u32 v61, v41, v61, s35
	v_and_or_b32 v45, v61, s42, v45
	global_store_dwordx2 v[56:57], v[44:45], off offset:-1024
	v_pk_mul_f32 v[44:45], v[62:63], v[50:51] op_sel_hi:[1,0]
	v_pk_mul_f32 v[62:63], v[36:37], v[50:51] op_sel_hi:[1,0]
	v_pk_fma_f32 v[36:37], v[18:19], v[44:45], v[26:27]
	v_pk_fma_f32 v[44:45], v[16:17], v[62:63], v[24:25]
	v_bfe_u32 v63, v37, 16, 1
	v_bfe_u32 v61, v44, 16, 1
	v_add3_u32 v61, v44, v61, s35
	v_bfe_u32 v62, v45, 16, 1
	v_lshrrev_b32_e32 v61, 16, v61
	v_add3_u32 v62, v45, v62, s35
	v_and_or_b32 v62, v62, s42, v61
	v_bfe_u32 v61, v36, 16, 1
	v_add3_u32 v61, v36, v61, s35
	v_lshrrev_b32_e32 v61, 16, v61
	v_add3_u32 v63, v37, v63, s35
	v_and_or_b32 v63, v63, s42, v61
	global_store_dwordx2 v[56:57], v[62:63], off offset:-512
	v_pk_mul_f32 v[46:47], v[46:47], v[50:51] op_sel_hi:[1,0]
	v_pk_mul_f32 v[62:63], v[32:33], v[50:51] op_sel_hi:[1,0]
	v_pk_fma_f32 v[32:33], v[22:23], v[46:47], v[30:31]
	v_pk_fma_f32 v[46:47], v[20:21], v[62:63], v[28:29]
	v_bfe_u32 v71, v33, 16, 1
	v_bfe_u32 v50, v46, 16, 1
	v_add3_u32 v50, v46, v50, s35
	v_bfe_u32 v61, v47, 16, 1
	v_lshrrev_b32_e32 v50, 16, v50
	v_add3_u32 v61, v47, v61, s35
	v_and_or_b32 v72, v61, s42, v50
	v_bfe_u32 v50, v32, 16, 1
	v_add3_u32 v50, v32, v50, s35
	v_lshrrev_b32_e32 v61, 16, v50
	v_add_u32_e32 v50, 0, v48
	ds_read_b128 v[62:65], v50
	v_add3_u32 v71, v33, v71, s35
	v_and_or_b32 v73, v71, s42, v61
	global_store_dwordx2 v[56:57], v[72:73], off
	ds_read_b128 v[72:75], v50 offset:1024
	s_waitcnt lgkmcnt(1)
	v_mul_f32_e32 v61, v39, v63
	v_fmac_f32_e32 v61, v38, v62
	v_mul_f32_e32 v62, v35, v65
	v_fmac_f32_e32 v62, v34, v64
	v_add_f32_e32 v61, v61, v62
	ds_read_b128 v[62:65], v50 offset:2048
	s_waitcnt lgkmcnt(1)
	v_mul_f32_e32 v71, v43, v73
	v_fmac_f32_e32 v71, v42, v72
	v_mul_f32_e32 v72, v41, v75
	v_fmac_f32_e32 v72, v40, v74
	v_add_f32_e32 v71, v71, v72
	ds_read_b128 v[72:75], v50 offset:3072
	s_waitcnt lgkmcnt(1)
	v_mul_f32_e32 v63, v45, v63
	v_fmac_f32_e32 v63, v44, v62
	v_mul_f32_e32 v62, v37, v65
	v_add_f32_e32 v61, 0, v61
	v_fmac_f32_e32 v62, v36, v64
	v_add_f32_e32 v61, v61, v71
	v_add_f32_e32 v62, v63, v62
	v_add_f32_e32 v61, v61, v62
	s_waitcnt lgkmcnt(0)
	v_mul_f32_e32 v62, v47, v73
	v_mul_f32_e32 v63, v33, v75
	v_fmac_f32_e32 v62, v46, v72
	v_fmac_f32_e32 v63, v32, v74
	v_add_f32_e32 v62, v62, v63
	v_add_f32_e32 v61, v61, v62
	ds_read_b128 v[62:65], v50 offset:4096
	ds_read_b128 v[72:75], v50 offset:5120
	s_nop 1
	v_mov_b32_dpp v71, v61 quad_perm:[1,0,3,2] row_mask:0xf bank_mask:0xf
	s_waitcnt lgkmcnt(1)
	v_mul_f32_e32 v63, v39, v63
	v_fmac_f32_e32 v63, v38, v62
	v_mul_f32_e32 v62, v35, v65
	v_fmac_f32_e32 v62, v34, v64
	v_add_f32_e32 v62, v63, v62
	s_waitcnt lgkmcnt(0)
	v_mul_f32_e32 v73, v43, v73
	v_add_f32_e32 v81, 0, v62
	v_fmac_f32_e32 v73, v42, v72
	v_mul_f32_e32 v72, v41, v75
	ds_read_b128 v[62:65], v50 offset:6144
	v_fmac_f32_e32 v72, v40, v74
	v_add_f32_e32 v72, v73, v72
	v_add_f32_e32 v81, v81, v72
	ds_read_b128 v[72:75], v50 offset:7168
	s_waitcnt lgkmcnt(1)
	v_mul_f32_e32 v63, v45, v63
	v_fmac_f32_e32 v63, v44, v62
	v_mul_f32_e32 v62, v37, v65
	v_fmac_f32_e32 v62, v36, v64
	v_add_f32_e32 v62, v63, v62
	s_waitcnt lgkmcnt(0)
	v_mul_f32_e32 v63, v47, v73
	v_mul_f32_e32 v64, v33, v75
	v_fmac_f32_e32 v63, v46, v72
	v_fmac_f32_e32 v64, v32, v74
	v_add_f32_e32 v62, v81, v62
	v_add_f32_e32 v63, v63, v64
	v_add_f32_e32 v62, v62, v63
	s_nop 1
	v_mov_b32_dpp v63, v62 quad_perm:[1,0,3,2] row_mask:0xf bank_mask:0xf
	v_add_f32_e32 v61, v61, v71
	s_nop 1
	v_mov_b32_dpp v64, v61 quad_perm:[2,3,0,1] row_mask:0xf bank_mask:0xf
	v_add_f32_e32 v62, v62, v63
	v_add_f32_e32 v61, v61, v64
	s_nop 1
	v_mov_b32_dpp v63, v62 quad_perm:[2,3,0,1] row_mask:0xf bank_mask:0xf
	s_nop 1
	v_mov_b32_dpp v64, v61 row_shl:4 row_mask:0xf bank_mask:0x5
	v_mov_b32_dpp v64, v61 row_shr:4 row_mask:0xf bank_mask:0xa
	v_add_f32_e32 v62, v62, v63
	v_add_f32_e32 v61, v61, v64
	s_nop 1
	v_mov_b32_dpp v63, v62 row_shl:4 row_mask:0xf bank_mask:0x5
	v_mov_b32_dpp v63, v62 row_shr:4 row_mask:0xf bank_mask:0xa
	s_nop 1
	v_mov_b32_dpp v64, v61 row_ror:8 row_mask:0xf bank_mask:0xf
	v_add_f32_e32 v62, v62, v63
	v_add_f32_e32 v61, v61, v64
	s_nop 1
	v_mov_b32_dpp v63, v62 row_ror:8 row_mask:0xf bank_mask:0xf
	v_mov_b32_e32 v64, v61
	v_mov_b32_e32 v120, v61
	s_nop 1
	v_permlane16_swap_b32_e32 v64, v120
	v_cndmask_b32_e64 v64, v120, v64, s[98:99]
	v_add_f32_e32 v63, v62, v63
	v_add_f32_e32 v61, v61, v64
	v_mov_b32_e32 v65, v63
	v_mov_b32_e32 v120, v63
	s_nop 1
	v_permlane16_swap_b32_e32 v65, v120
	v_cndmask_b32_e64 v65, v120, v65, s[98:99]
	ds_read_b128 v[72:75], v50 offset:8192
	ds_read_b128 v[76:79], v50 offset:9216
	v_add_f32_e32 v63, v63, v65
	s_waitcnt lgkmcnt(1)
; __device__ __forceinline__ float shx(float v, int o) { const int l = lane_now(); return __int_as_float(__builtin_amdgcn_ds_bpermute((l ^ o) << 2, __float_as_int(v))); }
; #define LAS __attribute__((address_space(3)))
; __device__ __forceinline__ float wave_sum(float v) {
; #pragma unroll
;     for (int o = 1; o < 64; o <<= 1) v += shx(v, o);
;     return v;
; template <int SRC, int EXTRA, bool OUT8 = false> ...
;     ...
;             for (int e = 0; e < 8; ++e) { float a = 0.f;
; #pragma unroll
;                 for (int j = 0; j < 4; ++j) { const f32x4 w = *(const LAS f32x4*)(w8s + e * 1024 + 256 * j + 4 * lane); a += (v[j].x * w.x + v[j].y * w.y) + (v[j].z * w.z + v[j].w * w.w); }
;                 d[e] = wave_sum(a); }
	v_mul_f32_e32 v65, v39, v73
	v_mul_f32_e32 v71, v35, v75
	v_fmac_f32_e32 v65, v38, v72
	v_fmac_f32_e32 v71, v34, v74
	ds_read_b128 v[72:75], v50 offset:10240
	v_add_f32_e32 v65, v65, v71
	s_waitcnt lgkmcnt(1)
	v_mul_f32_e32 v71, v43, v77
	v_fmac_f32_e32 v71, v42, v76
	v_mul_f32_e32 v76, v41, v79
	v_fmac_f32_e32 v76, v40, v78
	v_add_f32_e32 v65, 0, v65
	v_add_f32_e32 v71, v71, v76
	ds_read_b128 v[76:79], v50 offset:11264
	v_add_f32_e32 v65, v65, v71
	s_waitcnt lgkmcnt(1)
	v_mul_f32_e32 v71, v45, v73
	v_fmac_f32_e32 v71, v44, v72
	v_mul_f32_e32 v72, v37, v75
	v_fmac_f32_e32 v72, v36, v74
	v_add_f32_e32 v71, v71, v72
	v_add_f32_e32 v65, v65, v71
	s_waitcnt lgkmcnt(0)
	v_mul_f32_e32 v71, v47, v77
	v_mul_f32_e32 v72, v33, v79
	v_fmac_f32_e32 v71, v46, v76
	v_fmac_f32_e32 v72, v32, v78
	v_add_f32_e32 v71, v71, v72
	v_add_f32_e32 v65, v65, v71
	ds_read_b128 v[72:75], v50 offset:12288
	ds_read_b128 v[76:79], v50 offset:13312
	s_nop 1
	v_mov_b32_dpp v71, v65 quad_perm:[1,0,3,2] row_mask:0xf bank_mask:0xf
	s_waitcnt lgkmcnt(1)
	v_mul_f32_e32 v73, v39, v73
	v_fmac_f32_e32 v73, v38, v72
	v_mul_f32_e32 v72, v35, v75
	v_fmac_f32_e32 v72, v34, v74
	v_add_f32_e32 v72, v73, v72
	s_waitcnt lgkmcnt(0)
	v_mul_f32_e32 v77, v43, v77
	v_add_f32_e32 v85, 0, v72
	v_fmac_f32_e32 v77, v42, v76
	v_mul_f32_e32 v76, v41, v79
	ds_read_b128 v[72:75], v50 offset:14336
	v_fmac_f32_e32 v76, v40, v78
	v_add_f32_e32 v76, v77, v76
	v_add_f32_e32 v85, v85, v76
	ds_read_b128 v[76:79], v50 offset:15360
	s_waitcnt lgkmcnt(1)
	v_mul_f32_e32 v73, v45, v73
	v_fmac_f32_e32 v73, v44, v72
	v_mul_f32_e32 v72, v37, v75
	v_fmac_f32_e32 v72, v36, v74
	v_add_f32_e32 v72, v73, v72
	s_waitcnt lgkmcnt(0)
	v_mul_f32_e32 v73, v47, v77
	v_mul_f32_e32 v74, v33, v79
	v_fmac_f32_e32 v73, v46, v76
	v_fmac_f32_e32 v74, v32, v78
	v_add_f32_e32 v72, v85, v72
	v_add_f32_e32 v73, v73, v74
	v_add_f32_e32 v72, v72, v73
	v_add_f32_e32 v65, v65, v71
	s_nop 1
	v_mov_b32_dpp v73, v72 quad_perm:[1,0,3,2] row_mask:0xf bank_mask:0xf
	s_nop 1
	v_mov_b32_dpp v71, v65 quad_perm:[2,3,0,1] row_mask:0xf bank_mask:0xf
	v_add_f32_e32 v72, v72, v73
	s_nop 1
	v_mov_b32_dpp v73, v72 quad_perm:[2,3,0,1] row_mask:0xf bank_mask:0xf
	v_add_f32_e32 v65, v65, v71
	s_nop 1
	v_mov_b32_dpp v71, v65 row_shl:4 row_mask:0xf bank_mask:0x5
	v_mov_b32_dpp v71, v65 row_shr:4 row_mask:0xf bank_mask:0xa
	v_add_f32_e32 v72, v72, v73
	v_mov_b32_e32 v62, v61
	v_mov_b32_e32 v120, v61
	s_nop 1
	v_permlane32_swap_b32_e32 v62, v120
	v_cndmask_b32_e64 v62, v120, v62, s[100:101]
	s_nop 1
	v_mov_b32_dpp v73, v72 row_shl:4 row_mask:0xf bank_mask:0x5
	v_mov_b32_dpp v73, v72 row_shr:4 row_mask:0xf bank_mask:0xa
	v_add_f32_e32 v65, v65, v71
	s_nop 1
	v_mov_b32_dpp v71, v65 row_ror:8 row_mask:0xf bank_mask:0xf
	v_add_f32_e32 v72, v72, v73
	v_mov_b32_e32 v64, v63
	v_mov_b32_e32 v120, v63
	s_nop 1
	v_permlane32_swap_b32_e32 v64, v120
	v_cndmask_b32_e64 v64, v120, v64, s[100:101]
	s_nop 1
	v_mov_b32_dpp v73, v72 row_ror:8 row_mask:0xf bank_mask:0xf
	v_add_f32_e32 v65, v65, v71
	v_mov_b32_e32 v71, v65
	v_mov_b32_e32 v120, v65
	s_nop 1
	v_permlane16_swap_b32_e32 v71, v120
	v_cndmask_b32_e64 v71, v120, v71, s[98:99]
	v_add_f32_e32 v72, v72, v73
	v_add_f32_e32 v65, v65, v71
	v_mov_b32_e32 v73, v72
	v_mov_b32_e32 v120, v72
	s_nop 1
	v_permlane16_swap_b32_e32 v73, v120
	v_cndmask_b32_e64 v73, v120, v73, s[98:99]
	v_mov_b32_e32 v71, v65
	v_mov_b32_e32 v120, v65
	s_nop 1
	v_permlane32_swap_b32_e32 v71, v120
	v_cndmask_b32_e64 v71, v120, v71, s[100:101]
	v_add_f32_e32 v72, v72, v73
	ds_read_b128 v[74:77], v50 offset:16384
	ds_read_b128 v[78:81], v50 offset:17408
	v_mov_b32_e32 v73, v72
	v_mov_b32_e32 v120, v72
	s_nop 1
	v_permlane32_swap_b32_e32 v73, v120
	v_cndmask_b32_e64 v73, v120, v73, s[100:101]
	s_waitcnt lgkmcnt(1)
	v_mul_f32_e32 v75, v39, v75
	v_fmac_f32_e32 v75, v38, v74
	v_mul_f32_e32 v74, v35, v77
	v_fmac_f32_e32 v74, v34, v76
	v_add_f32_e32 v74, v75, v74
	s_waitcnt lgkmcnt(0)
	v_mul_f32_e32 v79, v43, v79
	v_add_f32_e32 v82, 0, v74
	v_fmac_f32_e32 v79, v42, v78
	v_mul_f32_e32 v78, v41, v81
	ds_read_b128 v[74:77], v50 offset:18432
	v_fmac_f32_e32 v78, v40, v80
	v_add_f32_e32 v78, v79, v78
	v_add_f32_e32 v82, v82, v78
	ds_read_b128 v[78:81], v50 offset:19456
	s_waitcnt lgkmcnt(1)
	v_mul_f32_e32 v75, v45, v75
	v_fmac_f32_e32 v75, v44, v74
	v_mul_f32_e32 v74, v37, v77
	v_fmac_f32_e32 v74, v36, v76
	v_add_f32_e32 v74, v75, v74
	s_waitcnt lgkmcnt(0)
	v_mul_f32_e32 v75, v47, v79
	v_mul_f32_e32 v76, v33, v81
	v_fmac_f32_e32 v75, v46, v78
	v_fmac_f32_e32 v76, v32, v80
	v_add_f32_e32 v74, v82, v74
	v_add_f32_e32 v75, v75, v76
	v_add_f32_e32 v82, v74, v75
	ds_read_b128 v[74:77], v50 offset:20480
	s_nop 1
	v_mov_b32_dpp v88, v82 quad_perm:[1,0,3,2] row_mask:0xf bank_mask:0xf
	ds_read_b128 v[78:81], v50 offset:21504
	s_waitcnt lgkmcnt(1)
	v_mul_f32_e32 v75, v39, v75
	v_fmac_f32_e32 v75, v38, v74
	v_mul_f32_e32 v74, v35, v77
	v_fmac_f32_e32 v74, v34, v76
	v_add_f32_e32 v74, v75, v74
	s_waitcnt lgkmcnt(0)
	v_mul_f32_e32 v79, v43, v79
	v_add_f32_e32 v89, 0, v74
	v_fmac_f32_e32 v79, v42, v78
	v_mul_f32_e32 v78, v41, v81
	ds_read_b128 v[74:77], v50 offset:22528
	v_fmac_f32_e32 v78, v40, v80
	v_add_f32_e32 v78, v79, v78
	v_add_f32_e32 v89, v89, v78
	ds_read_b128 v[78:81], v50 offset:23552
	s_waitcnt lgkmcnt(1)
	v_mul_f32_e32 v75, v45, v75
	v_fmac_f32_e32 v75, v44, v74
	v_mul_f32_e32 v74, v37, v77
	v_fmac_f32_e32 v74, v36, v76
	v_add_f32_e32 v74, v75, v74
	s_waitcnt lgkmcnt(0)
; __device__ __forceinline__ float shx(float v, int o) { const int l = lane_now(); return __int_as_float(__builtin_amdgcn_ds_bpermute((l ^ o) << 2, __float_as_int(v))); }
; #define LAS __attribute__((address_space(3)))
; __device__ __forceinline__ float wave_sum(float v) {
; #pragma unroll
;     for (int o = 1; o < 64; o <<= 1) v += shx(v, o);
;     return v;
; template <int SRC, int EXTRA, bool OUT8 = false> ...
;     ...
;             for (int e = 0; e < 8; ++e) { float a = 0.f;
; #pragma unroll
;                 for (int j = 0; j < 4; ++j) { const f32x4 w = *(const LAS f32x4*)(w8s + e * 1024 + 256 * j + 4 * lane); a += (v[j].x * w.x + v[j].y * w.y) + (v[j].z * w.z + v[j].w * w.w); }
;                 d[e] = wave_sum(a); }
	v_mul_f32_e32 v75, v47, v79
	v_mul_f32_e32 v76, v33, v81
	v_fmac_f32_e32 v75, v46, v78
	v_fmac_f32_e32 v76, v32, v80
	v_add_f32_e32 v74, v89, v74
	v_add_f32_e32 v75, v75, v76
	v_add_f32_e32 v74, v74, v75
	s_nop 1
	v_mov_b32_dpp v75, v74 quad_perm:[1,0,3,2] row_mask:0xf bank_mask:0xf
	v_add_f32_e32 v76, v82, v88
	s_nop 1
	v_mov_b32_dpp v77, v76 quad_perm:[2,3,0,1] row_mask:0xf bank_mask:0xf
	v_add_f32_e32 v74, v74, v75
	v_add_f32_e32 v76, v76, v77
	s_nop 1
	v_mov_b32_dpp v75, v74 quad_perm:[2,3,0,1] row_mask:0xf bank_mask:0xf
	s_nop 1
	v_mov_b32_dpp v77, v76 row_shl:4 row_mask:0xf bank_mask:0x5
	v_mov_b32_dpp v77, v76 row_shr:4 row_mask:0xf bank_mask:0xa
	v_add_f32_e32 v74, v74, v75
	v_add_f32_e32 v76, v76, v77
	s_nop 1
	v_mov_b32_dpp v75, v74 row_shl:4 row_mask:0xf bank_mask:0x5
	v_mov_b32_dpp v75, v74 row_shr:4 row_mask:0xf bank_mask:0xa
	s_nop 1
	v_mov_b32_dpp v77, v76 row_ror:8 row_mask:0xf bank_mask:0xf
	v_add_f32_e32 v74, v74, v75
	v_add_f32_e32 v76, v76, v77
	s_nop 1
	v_mov_b32_dpp v75, v74 row_ror:8 row_mask:0xf bank_mask:0xf
	v_mov_b32_e32 v77, v76
	v_mov_b32_e32 v120, v76
	s_nop 1
	v_permlane16_swap_b32_e32 v77, v120
	v_cndmask_b32_e64 v77, v120, v77, s[98:99]
	v_add_f32_e32 v78, v74, v75
	v_mov_b32_e32 v79, v78
	v_mov_b32_e32 v120, v78
	s_nop 1
	v_permlane16_swap_b32_e32 v79, v120
	v_cndmask_b32_e64 v79, v120, v79, s[98:99]
	v_add_f32_e32 v74, v76, v77
	ds_read_b128 v[82:85], v50 offset:25600
	v_add_f32_e32 v76, v78, v79
	ds_read_b128 v[78:81], v50 offset:24576
	s_waitcnt lgkmcnt(1)
	v_mul_f32_e32 v83, v43, v83
	v_fmac_f32_e32 v83, v42, v82
	v_mul_f32_e32 v82, v41, v85
	s_waitcnt lgkmcnt(0)
	v_mul_f32_e32 v79, v39, v79
	v_fmac_f32_e32 v79, v38, v78
	v_mul_f32_e32 v78, v35, v81
	v_fmac_f32_e32 v78, v34, v80
	v_add_f32_e32 v78, v79, v78
	v_add_f32_e32 v86, 0, v78
	ds_read_b128 v[78:81], v50 offset:26624
	v_fmac_f32_e32 v82, v40, v84
	v_add_f32_e32 v82, v83, v82
	v_add_f32_e32 v86, v86, v82
	ds_read_b128 v[82:85], v50 offset:27648
	s_waitcnt lgkmcnt(1)
	v_mul_f32_e32 v79, v45, v79
	v_fmac_f32_e32 v79, v44, v78
	v_mul_f32_e32 v78, v37, v81
	v_fmac_f32_e32 v78, v36, v80
	v_add_f32_e32 v78, v79, v78
	s_waitcnt lgkmcnt(0)
	v_mul_f32_e32 v79, v47, v83
	v_mul_f32_e32 v80, v33, v85
	v_fmac_f32_e32 v79, v46, v82
	v_fmac_f32_e32 v80, v32, v84
	v_add_f32_e32 v78, v86, v78
	v_add_f32_e32 v79, v79, v80
	v_add_f32_e32 v86, v78, v79
	v_mbcnt_lo_u32_b32 v87, -1, 0
	v_mbcnt_hi_u32_b32 v87, -1, v87
	v_mbcnt_lo_u32_b32 v88, -1, 0
	v_mbcnt_hi_u32_b32 v88, -1, v88
	v_mbcnt_lo_u32_b32 v89, -1, 0
	v_mbcnt_hi_u32_b32 v89, -1, v89
	v_mbcnt_lo_u32_b32 v90, -1, 0
	v_mbcnt_hi_u32_b32 v90, -1, v90
	v_mbcnt_lo_u32_b32 v91, -1, 0
	v_mbcnt_hi_u32_b32 v91, -1, v91
	ds_read_b128 v[78:81], v50 offset:28672
	s_nop 1
	v_mov_b32_dpp v92, v86 quad_perm:[1,0,3,2] row_mask:0xf bank_mask:0xf
	ds_read_b128 v[82:85], v50 offset:29696
	s_waitcnt lgkmcnt(1)
	v_mul_f32_e32 v39, v39, v79
	v_mul_f32_e32 v35, v35, v81
	v_fmac_f32_e32 v39, v38, v78
	v_fmac_f32_e32 v35, v34, v80
	ds_read_b128 v[78:81], v50 offset:30720
	v_add_f32_e32 v34, v39, v35
	s_waitcnt lgkmcnt(1)
	v_mul_f32_e32 v35, v43, v83
	v_mul_f32_e32 v38, v41, v85
	v_fmac_f32_e32 v35, v42, v82
	v_fmac_f32_e32 v38, v40, v84
	v_add_f32_e32 v35, v35, v38
	ds_read_b128 v[38:41], v50 offset:31744
	v_add_f32_e32 v34, 0, v34
	v_add_f32_e32 v34, v34, v35
	s_waitcnt lgkmcnt(1)
	v_mul_f32_e32 v35, v45, v79
	v_mul_f32_e32 v37, v37, v81
	v_fmac_f32_e32 v35, v44, v78
	v_fmac_f32_e32 v37, v36, v80
	v_add_f32_e32 v35, v35, v37
	v_add_f32_e32 v34, v34, v35
	s_waitcnt lgkmcnt(0)
	v_mul_f32_e32 v35, v47, v39
	v_mul_f32_e32 v33, v33, v41
	v_fmac_f32_e32 v35, v46, v38
	v_fmac_f32_e32 v33, v32, v40
	v_add_f32_e32 v32, v35, v33
	v_add_f32_e32 v32, v34, v32
	s_nop 1
	v_mov_b32_dpp v33, v32 quad_perm:[1,0,3,2] row_mask:0xf bank_mask:0xf
	v_add_f32_e32 v34, v86, v92
	s_nop 1
	v_mov_b32_dpp v35, v34 quad_perm:[2,3,0,1] row_mask:0xf bank_mask:0xf
	v_add_f32_e32 v32, v32, v33
	s_nop 1
	v_mov_b32_dpp v33, v32 quad_perm:[2,3,0,1] row_mask:0xf bank_mask:0xf
	v_add_f32_e32 v34, v34, v35
	s_nop 1
	v_mov_b32_dpp v35, v34 row_shl:4 row_mask:0xf bank_mask:0x5
	v_mov_b32_dpp v35, v34 row_shr:4 row_mask:0xf bank_mask:0xa
	v_add_f32_e32 v32, v32, v33
	v_mov_b32_e32 v75, v74
	v_mov_b32_e32 v120, v74
	s_nop 1
	v_permlane32_swap_b32_e32 v75, v120
	v_cndmask_b32_e64 v75, v120, v75, s[100:101]
	s_nop 1
	v_mov_b32_dpp v33, v32 row_shl:4 row_mask:0xf bank_mask:0x5
	v_mov_b32_dpp v33, v32 row_shr:4 row_mask:0xf bank_mask:0xa
	v_add_f32_e32 v34, v34, v35
	s_nop 1
	v_mov_b32_dpp v35, v34 row_ror:8 row_mask:0xf bank_mask:0xf
	v_add_f32_e32 v32, v32, v33
	v_mov_b32_e32 v77, v76
	v_mov_b32_e32 v120, v76
	s_nop 1
	v_permlane32_swap_b32_e32 v77, v120
	v_cndmask_b32_e64 v77, v120, v77, s[100:101]
	s_nop 1
	v_mov_b32_dpp v33, v32 row_ror:8 row_mask:0xf bank_mask:0xf
	v_add_f32_e32 v34, v34, v35
	v_mov_b32_e32 v35, v34
	v_mov_b32_e32 v120, v34
	s_nop 1
	v_permlane16_swap_b32_e32 v35, v120
	v_cndmask_b32_e64 v35, v120, v35, s[98:99]
	v_add_f32_e32 v36, v32, v33
	v_mov_b32_e32 v37, v36
	v_mov_b32_e32 v120, v36
	s_nop 1
	v_permlane16_swap_b32_e32 v37, v120
	v_cndmask_b32_e64 v37, v120, v37, s[98:99]
	v_add_f32_e32 v32, v34, v35
	v_add_f32_e32 v34, v36, v37
	v_mov_b32_e32 v33, v32
	v_mov_b32_e32 v120, v32
	s_nop 1
	v_permlane32_swap_b32_e32 v33, v120
	v_cndmask_b32_e64 v33, v120, v33, s[100:101]
	v_mov_b32_e32 v35, v34
	v_mov_b32_e32 v120, v34
	s_nop 1
	v_permlane32_swap_b32_e32 v35, v120
	v_cndmask_b32_e64 v35, v120, v35, s[100:101]
	s_and_saveexec_b64 s[28:29], s[12:13]
	s_cbranch_execz .LBB0_1056
; template <int SRC, int EXTRA, bool OUT8 = false> ...
;     ...
;             if (EXTRA == 1) {
;                 float x = d[0];
; #pragma unroll
;                 for (int e = 1; e < 8; ++e) x = (lane == e) ? d[e] : x;
;                 if (lane < 8) { x += bf8[lane]; const float ls = (x >= 0.f) ? -log1pf(__expf(-x)) : (x - log1pf(__expf(x))); logf[(size_t)lane * M + row] = ls; }
	global_load_dword v36, v[52:53], off offset:32
	v_add_f32_e32 v39, v63, v64
	v_add_f32_e32 v40, v61, v62
	v_add_f32_e32 v38, v65, v71
	v_cndmask_b32_e64 v39, v40, v39, s[26:27]
	v_add_f32_e32 v37, v72, v73
	v_cndmask_b32_e64 v38, v39, v38, s[24:25]
	v_add_f32_e32 v34, v34, v35
	v_add_f32_e32 v35, v74, v75
	v_cndmask_b32_e64 v37, v38, v37, s[22:23]
	v_add_f32_e32 v32, v32, v33
	v_add_f32_e32 v33, v76, v77
	v_cndmask_b32_e64 v35, v37, v35, s[20:21]
	v_cndmask_b32_e64 v33, v35, v33, s[18:19]
	v_cndmask_b32_e64 v32, v33, v32, s[16:17]
	v_cndmask_b32_e64 v32, v32, v34, s[14:15]
	s_waitcnt vmcnt(0)
	v_add_f32_e32 v32, v32, v36
	v_cmp_le_f32_e32 vcc, 0, v32
	s_and_saveexec_b64 s[52:53], vcc
	s_xor_b64 s[52:53], exec, s[52:53]
	s_cbranch_execz .LBB0_1062
	v_mul_f32_e32 v32, 0xbfb8aa3b, v32
	v_exp_f32_e32 v46, v32
	s_nop 0
	v_add_f32_e32 v34, 1.0, v46
	v_frexp_mant_f32_e32 v36, v34
	v_cvt_f64_f32_e32 v[32:33], v34
	v_frexp_exp_i32_f64_e32 v32, v[32:33]
	v_cmp_gt_f32_e32 vcc, s43, v36
	v_add_f32_e32 v35, -1.0, v34
	v_sub_f32_e32 v37, v35, v34
	v_subbrev_co_u32_e32 v40, vcc, 0, v32, vcc
	v_sub_u32_e32 v32, 0, v40
	v_sub_f32_e32 v35, v46, v35
	v_add_f32_e32 v37, 1.0, v37
	v_ldexp_f32 v33, v34, v32
	v_add_f32_e32 v35, v35, v37
	v_add_f32_e32 v34, -1.0, v33
	v_add_f32_e32 v36, 1.0, v33
	v_ldexp_f32 v32, v35, v32
	v_add_f32_e32 v35, 1.0, v34
	v_add_f32_e32 v37, -1.0, v36
	v_sub_f32_e32 v35, v33, v35
	v_sub_f32_e32 v33, v33, v37
	v_add_f32_e32 v35, v32, v35
	v_add_f32_e32 v32, v32, v33
	v_add_f32_e32 v41, v36, v32
	v_rcp_f32_e32 v43, v41
	v_sub_f32_e32 v33, v41, v36
	v_sub_f32_e32 v42, v32, v33
	v_add_f32_e32 v33, v34, v35
	v_mul_f32_e32 v45, v33, v43
	v_sub_f32_e32 v32, v33, v34
	v_mul_f32_e32 v34, v41, v45
	v_fma_f32 v36, v45, v41, -v34
	v_fmac_f32_e32 v36, v45, v42
	v_sub_f32_e32 v44, v35, v32
	v_add_f32_e32 v32, v34, v36
	v_sub_f32_e32 v35, v33, v32
	v_pk_add_f32 v[38:39], v[32:33], v[34:35] neg_lo:[0,1] neg_hi:[0,1]
	v_mov_b32_e32 v37, v32
	v_pk_add_f32 v[32:33], v[38:39], v[36:37] neg_lo:[0,1] neg_hi:[0,1]
	v_cmp_neq_f32_e32 vcc, s55, v46
	v_add_f32_e32 v33, v44, v33
	v_add_f32_e32 v32, v32, v33
	v_add_f32_e32 v33, v35, v32
	v_mul_f32_e32 v44, v43, v33
	v_mul_f32_e32 v34, v41, v44
	v_fma_f32 v36, v44, v41, -v34
	v_fmac_f32_e32 v36, v44, v42
	v_sub_f32_e32 v35, v35, v33
	v_add_f32_e32 v41, v32, v35
	v_add_f32_e32 v32, v34, v36
	v_sub_f32_e32 v35, v33, v32
	v_pk_add_f32 v[38:39], v[32:33], v[34:35] neg_lo:[0,1] neg_hi:[0,1]
	v_mov_b32_e32 v37, v32
	v_pk_add_f32 v[32:33], v[38:39], v[36:37] neg_lo:[0,1] neg_hi:[0,1]
	s_nop 0
	v_add_f32_e32 v33, v41, v33
	v_add_f32_e32 v32, v32, v33
	v_add_f32_e32 v33, v45, v44
	v_add_f32_e32 v32, v35, v32
	v_sub_f32_e32 v34, v33, v45
	v_mul_f32_e32 v32, v43, v32
	v_sub_f32_e32 v34, v44, v34
	v_add_f32_e32 v34, v34, v32
	v_add_f32_e32 v36, v33, v34
	v_mul_f32_e32 v37, v36, v36
	v_fmamk_f32 v32, v37, 0x3e9b6dac, v67
	v_fmaak_f32 v61, v37, v32, 0x3f2aaada
	v_cvt_f32_i32_e32 v32, v40
	v_sub_f32_e32 v33, v36, v33
	v_sub_f32_e32 v33, v34, v33
	v_ldexp_f32 v38, v33, 1
	v_mul_f32_e32 v33, v36, v37
	v_ldexp_f32 v35, v36, 1
	v_pk_mul_f32 v[36:37], v[32:33], v[60:61]
	s_nop 0
	v_fma_f32 v34, v32, s54, -v36
	v_fmac_f32_e32 v34, 0xb102e308, v32
	v_pk_add_f32 v[32:33], v[36:37], v[34:35]
	s_nop 0
	v_sub_f32_e32 v35, v33, v35
	v_sub_f32_e32 v35, v37, v35
	v_add_f32_e32 v39, v38, v35
	v_mov_b32_e32 v38, v36
	v_pk_add_f32 v[36:37], v[32:33], v[36:37] neg_lo:[0,1] neg_hi:[0,1]
	v_pk_add_f32 v[40:41], v[32:33], v[38:39]
	v_mov_b32_e32 v35, v32
	v_mov_b32_e32 v37, v41
	v_pk_add_f32 v[42:43], v[34:35], v[36:37] neg_lo:[0,1] neg_hi:[0,1]
	v_pk_add_f32 v[34:35], v[34:35], v[36:37]
	v_mov_b32_e32 v38, v39
	v_pk_add_f32 v[36:37], v[34:35], v[32:33] op_sel:[1,0] op_sel_hi:[0,1] neg_lo:[0,1] neg_hi:[0,1]
	v_pk_add_f32 v[44:45], v[40:41], v[36:37] op_sel_hi:[1,0] neg_lo:[0,1] neg_hi:[0,1]
	v_mov_b32_e32 v40, v41
	v_mov_b32_e32 v41, v35
	v_pk_mov_b32 v[36:37], v[32:33], v[36:37] op_sel:[1,0]
	v_mov_b32_e32 v39, v32
	v_pk_add_f32 v[36:37], v[40:41], v[36:37] neg_lo:[0,1] neg_hi:[0,1]
	v_mov_b32_e32 v44, v42
	v_pk_add_f32 v[32:33], v[38:39], v[36:37] neg_lo:[0,1] neg_hi:[0,1]
	v_mov_b32_e32 v43, v35
	v_pk_add_f32 v[36:37], v[44:45], v[32:33]
	s_nop 0
	v_pk_add_f32 v[38:39], v[36:37], v[36:37] op_sel:[0,1] op_sel_hi:[1,0]
	s_nop 0
	v_pk_add_f32 v[34:35], v[34:35], v[38:39] op_sel:[1,0] op_sel_hi:[0,1]
	v_mov_b32_e32 v37, v34
	v_pk_add_f32 v[40:41], v[36:37], v[42:43] neg_lo:[0,1] neg_hi:[0,1]
	v_mov_b32_e32 v33, v38
	v_sub_f32_e32 v35, v36, v40
	v_pk_add_f32 v[32:33], v[32:33], v[40:41] neg_lo:[0,1] neg_hi:[0,1]
	v_sub_f32_e32 v35, v42, v35
	v_add_f32_e32 v32, v32, v35
	v_add_f32_e32 v32, v32, v33
	v_add_f32_e32 v32, v34, v32
	v_cndmask_b32_e32 v32, v68, v32, vcc
	v_cmp_ngt_f32_e32 vcc, -1.0, v46
	s_nop 1
	v_cndmask_b32_e32 v32, v69, v32, vcc
	v_cmp_neq_f32_e32 vcc, -1.0, v46
	s_nop 1
	v_cndmask_b32_e32 v32, v70, v32, vcc
	v_cmp_lt_f32_e64 vcc, |v46|, s56
	s_nop 1
	v_cndmask_b32_e32 v32, v32, v46, vcc
	v_xor_b32_e32 v33, 0x80000000, v32

; __device__ __forceinline__ float shx(float v, int o) { const int l = lane_now(); return __int_as_float(__builtin_amdgcn_ds_bpermute((l ^ o) << 2, __float_as_int(v))); }
; __device__ __forceinline__ float wave_sum(float v) {
; #pragma unroll
;     for (int o = 1; o < 64; o <<= 1) v += shx(v, o);
;     return v;
; template <int SRC, int EXTRA, bool OUT8 = false> ...
;     ...
;         float s = 0.f;
; #pragma unroll
;         for (int j = 0; j < 4; ++j) s += (v[j].x + v[j].y) + (v[j].z + v[j].w);
;         const float mean = wave_sum(s) * (1.f / 1024.f); float s2 = 0.f;
; #pragma unroll
;         for (int j = 0; j < 4; ++j) { v[j] = v[j] - mean; s2 += (v[j].x * v[j].x + v[j].y * v[j].y) + (v[j].z * v[j].z + v[j].w * v[j].w); }
;         const float rstd = 1.f / sqrtf(wave_sum(s2) * (1.f / 1024.f) + LN_EPS);
;         if (stats && lane == 0) { stats[2 * row] = mean; stats[2 * row + 1] = rstd; }
.LBB0_1896:
	global_load_dwordx4 v[44:47], v[54:55], off offset:-3072
	global_load_dwordx4 v[40:43], v[54:55], off offset:-2048
	global_load_dwordx4 v[36:39], v[54:55], off offset:-1024
	s_waitcnt lgkmcnt(0)
	global_load_dwordx4 v[32:35], v[54:55], off
	s_waitcnt vmcnt(3)
	v_mov_b32_e32 v57, v46
	v_mov_b32_e32 v56, v45
	v_mov_b32_e32 v58, v44
	v_mov_b32_e32 v59, v47
	s_waitcnt vmcnt(2)
	v_mov_b32_e32 v66, v41
	v_mov_b32_e32 v67, v42
	v_mov_b32_e32 v68, v40
	v_mov_b32_e32 v69, v43
	v_pk_add_f32 v[56:57], v[56:57], v[58:59]
	v_pk_add_f32 v[58:59], v[66:67], v[68:69]
	v_add_f32_e32 v65, v56, v57
	v_pk_add_f32 v[56:57], v[58:59], v[58:59] op_sel:[0,1] op_sel_hi:[1,0]
	s_waitcnt vmcnt(1)
	v_add_f32_e32 v70, v36, v37
	v_add_f32_e32 v72, v38, v39
	s_waitcnt vmcnt(0)
	v_mov_b32_e32 v75, v32
	v_mov_b32_e32 v71, v34
	v_mov_b32_e32 v73, v35
	v_add_f32_e32 v74, 0, v65
	v_mov_b32_e32 v57, v33
	v_pk_add_f32 v[66:67], v[70:71], v[72:73]
	v_pk_add_f32 v[56:57], v[74:75], v[56:57]
	s_nop 0
	v_pk_add_f32 v[56:57], v[56:57], v[66:67]
	v_add_f32_e32 v56, v56, v57
	s_nop 1
	v_mov_b32_dpp v57, v56 quad_perm:[1,0,3,2] row_mask:0xf bank_mask:0xf
	v_add_f32_e32 v56, v56, v57
	s_nop 1
	v_mov_b32_dpp v57, v56 quad_perm:[2,3,0,1] row_mask:0xf bank_mask:0xf
	v_add_f32_e32 v56, v56, v57
	s_nop 1
	v_mov_b32_dpp v57, v56 row_shl:4 row_mask:0xf bank_mask:0x5
	v_mov_b32_dpp v57, v56 row_shr:4 row_mask:0xf bank_mask:0xa
	v_add_f32_e32 v56, v56, v57
	s_nop 1
	v_mov_b32_dpp v57, v56 row_ror:8 row_mask:0xf bank_mask:0xf
	v_add_f32_e32 v56, v56, v57
	v_mov_b32_e32 v57, v56
	v_mov_b32_e32 v120, v56
	s_nop 1
	v_permlane16_swap_b32_e32 v57, v120
	v_cndmask_b32_e64 v57, v120, v57, s[98:99]
	v_add_f32_e32 v56, v56, v57
	v_mov_b32_e32 v57, v56
	v_mov_b32_e32 v120, v56
	s_nop 1
	v_permlane32_swap_b32_e32 v57, v120
	v_cndmask_b32_e64 v57, v120, v57, s[100:101]
	v_add_f32_e32 v65, v56, v57
	v_fmamk_f32 v59, v65, 0xba800000, v47
	v_fmamk_f32 v45, v65, 0xba800000, v45
	v_fmamk_f32 v43, v65, 0xba800000, v43
	v_fmamk_f32 v41, v65, 0xba800000, v41
	v_fmamk_f32 v58, v65, 0xba800000, v46
	v_fmac_f32_e32 v44, 0xba800000, v65
	v_fmamk_f32 v42, v65, 0xba800000, v42
	v_fmac_f32_e32 v40, 0xba800000, v65
	v_fmamk_f32 v57, v65, 0xba800000, v39
	v_fmamk_f32 v56, v65, 0xba800000, v38
	v_fmamk_f32 v37, v65, 0xba800000, v37
	v_fmamk_f32 v47, v65, 0xba800000, v35
	v_fmamk_f32 v46, v65, 0xba800000, v34
	v_mul_f32_e32 v34, v45, v45
	v_mul_f32_e32 v35, v59, v59
	v_mul_f32_e32 v38, v41, v41
	v_mul_f32_e32 v39, v43, v43
	v_fmac_f32_e32 v36, 0xba800000, v65
	v_fmamk_f32 v33, v65, 0xba800000, v33
	v_mul_f32_e32 v66, v37, v37
	v_mul_f32_e32 v67, v57, v57
	v_fmac_f32_e32 v34, v44, v44
	v_fmac_f32_e32 v35, v58, v58
	v_fmac_f32_e32 v38, v40, v40
	v_fmac_f32_e32 v39, v42, v42
	v_fmac_f32_e32 v32, 0xba800000, v65
	v_mul_f32_e32 v68, v33, v33
	v_mul_f32_e32 v69, v47, v47
	v_fmac_f32_e32 v66, v36, v36
	v_fmac_f32_e32 v67, v56, v56
	v_add_f32_e32 v34, v34, v35
	v_add_f32_e32 v35, v38, v39
	v_fmac_f32_e32 v68, v32, v32
	v_fmac_f32_e32 v69, v46, v46
	v_add_f32_e32 v38, v66, v67
	v_add_f32_e32 v34, v34, v35
	v_add_f32_e32 v39, v68, v69
	v_add_f32_e32 v34, v38, v34
	v_add_f32_e32 v34, v39, v34
	s_nop 1
	v_mov_b32_dpp v35, v34 quad_perm:[1,0,3,2] row_mask:0xf bank_mask:0xf
	v_add_f32_e32 v34, v34, v35
	s_nop 1
	v_mov_b32_dpp v35, v34 quad_perm:[2,3,0,1] row_mask:0xf bank_mask:0xf
	v_add_f32_e32 v34, v34, v35
	s_nop 1
	v_mov_b32_dpp v35, v34 row_shl:4 row_mask:0xf bank_mask:0x5
	v_mov_b32_dpp v35, v34 row_shr:4 row_mask:0xf bank_mask:0xa
	v_add_f32_e32 v34, v34, v35
	s_nop 1
	v_mov_b32_dpp v35, v34 row_ror:8 row_mask:0xf bank_mask:0xf
	v_add_f32_e32 v34, v34, v35
	v_mov_b32_e32 v35, v34
	v_mov_b32_e32 v120, v34
	s_nop 1
	v_permlane16_swap_b32_e32 v35, v120
	v_cndmask_b32_e64 v35, v120, v35, s[98:99]
	v_add_f32_e32 v34, v34, v35
	v_mov_b32_e32 v35, v34
	v_mov_b32_e32 v120, v34
	s_nop 1
	v_permlane32_swap_b32_e32 v35, v120
	v_cndmask_b32_e64 v35, v120, v35, s[100:101]
	v_add_f32_e32 v34, v34, v35
	v_fmamk_f32 v34, v34, 0x3a800000, v61
	v_mul_f32_e32 v35, 0x4f800000, v34
	v_cmp_gt_f32_e32 vcc, s31, v34
	s_nop 1
	v_cndmask_b32_e32 v34, v34, v35, vcc
	v_sqrt_f32_e32 v35, v34
	s_nop 0
	v_add_u32_e32 v38, -1, v35
	v_add_u32_e32 v39, 1, v35
	v_fma_f32 v60, -v38, v35, v34
	v_fma_f32 v66, -v39, v35, v34
	v_cmp_ge_f32_e64 s[12:13], 0, v60
	s_nop 1
	v_cndmask_b32_e64 v35, v35, v38, s[12:13]
	v_cmp_lt_f32_e64 s[12:13], 0, v66
	s_nop 1
	v_cndmask_b32_e64 v35, v35, v39, s[12:13]
	v_mul_f32_e32 v38, 0x37800000, v35
	v_cndmask_b32_e32 v35, v35, v38, vcc
	v_cmp_class_f32_e32 vcc, v34, v62
	s_nop 1
	v_cndmask_b32_e32 v34, v35, v34, vcc
	v_div_scale_f32 v35, s[12:13], v34, v34, 1.0
	v_rcp_f32_e32 v38, v35
	v_div_scale_f32 v39, vcc, 1.0, v34, 1.0
	v_fma_f32 v60, -v35, v38, 1.0
	v_fmac_f32_e32 v38, v60, v38
	v_mul_f32_e32 v60, v39, v38
	v_fma_f32 v66, -v35, v60, v39
	v_fmac_f32_e32 v60, v66, v38
	v_fma_f32 v35, -v35, v60, v39
	v_div_fmas_f32 v35, v35, v38, v60
	v_div_fixup_f32 v60, v35, v34, 1.0
	s_and_saveexec_b64 s[12:13], s[10:11]
	s_cbranch_execz .LBB0_1898
	s_ashr_i32 s39, s38, 31
	s_lshl_b64 s[14:15], s[38:39], 2
	s_add_u32 s14, s3, s14
	v_mul_f32_e32 v34, 0x3a800000, v65
	s_addc_u32 s15, s50, s15
	v_mov_b32_e32 v35, v60
	global_store_dwordx2 v51, v[34:35], s[14:15]
; #define LAS __attribute__((address_space(3)))
; __device__ __forceinline__ unsigned pk2(float lo, float hi) { return f2bf(lo) | (f2bf(hi) << 16); }
; template <int SRC, int EXTRA, bool OUT8 = false> ...
;     ...
;         for (int j = 0; j < 4; ++j) { v[j] = v[j] * rstd * gv[j] + bv[j]; if (of32) *(f32x4*)(of32 + (size_t)row * 1024 + 256 * j + 4 * lane) = v[j];
;             if (obf) { if constexpr (OUT8) { int w = 0; w = __builtin_amdgcn_cvt_pk_fp8_f32(v[j].x, v[j].y, w, false); w = __builtin_amdgcn_cvt_pk_fp8_f32(v[j].z, v[j].w, w, true); *(unsigned*)((unsigned char*)obf + (size_t)row * 1024 + 256 * j + 4 * lane) = (unsigned)w; }
;                 else { v2u o; o.x = pk2(v[j].x, v[j].y); o.y = pk2(v[j].z, v[j].w); *(v2u*)(obf + (size_t)row * 1024 + 256 * j + 4 * lane) = o; } } }
;         if (EXTRA != 0) {
;             float d[8];
; #pragma unroll
;             for (int e = 0; e < 8; ++e) { float a = 0.f;
; #pragma unroll
;                 for (int j = 0; j < 4; ++j) { const f32x4 w = *(const LAS f32x4*)(w8s + e * 1024 + 256 * j + 4 * lane); a += (v[j].x * w.x + v[j].y * w.y) + (v[j].z * w.z + v[j].w * w.w); }
.LBB0_1898:
	s_or_b64 exec, exec, s[12:13]
	v_pk_mul_f32 v[38:39], v[44:45], v[60:61] op_sel_hi:[1,0]
	v_pk_mul_f32 v[34:35], v[58:59], v[60:61] op_sel_hi:[1,0]
	v_pk_fma_f32 v[38:39], v[0:1], v[38:39], v[4:5]
	v_pk_fma_f32 v[34:35], v[2:3], v[34:35], v[6:7]
	v_bfe_u32 v44, v38, 16, 1
	v_add3_u32 v44, v38, v44, s35
	v_bfe_u32 v45, v39, 16, 1
	v_lshrrev_b32_e32 v44, 16, v44
	v_add3_u32 v45, v39, v45, s35
	v_and_or_b32 v44, v45, s54, v44
	v_bfe_u32 v45, v34, 16, 1
	v_add3_u32 v45, v34, v45, s35
	v_bfe_u32 v58, v35, 16, 1
	v_lshrrev_b32_e32 v45, 16, v45
	v_add3_u32 v58, v35, v58, s35
	v_and_or_b32 v45, v58, s54, v45
	global_store_dwordx2 v[52:53], v[44:45], off offset:-1536
	v_pk_mul_f32 v[42:43], v[42:43], v[60:61] op_sel_hi:[1,0]
	v_pk_mul_f32 v[44:45], v[40:41], v[60:61] op_sel_hi:[1,0]
	v_pk_fma_f32 v[40:41], v[10:11], v[42:43], v[18:19]
	v_pk_fma_f32 v[42:43], v[8:9], v[44:45], v[16:17]
	v_bfe_u32 v58, v41, 16, 1
	v_bfe_u32 v44, v42, 16, 1
	v_add3_u32 v44, v42, v44, s35
	v_bfe_u32 v45, v43, 16, 1
	v_lshrrev_b32_e32 v44, 16, v44
	v_add3_u32 v45, v43, v45, s35
	v_and_or_b32 v44, v45, s54, v44
	v_bfe_u32 v45, v40, 16, 1
	v_add3_u32 v45, v40, v45, s35
	v_lshrrev_b32_e32 v45, 16, v45
	v_add3_u32 v58, v41, v58, s35
	v_and_or_b32 v45, v58, s54, v45
	global_store_dwordx2 v[52:53], v[44:45], off offset:-1024
	v_pk_mul_f32 v[44:45], v[56:57], v[60:61] op_sel_hi:[1,0]
	v_pk_mul_f32 v[56:57], v[36:37], v[60:61] op_sel_hi:[1,0]
	v_pk_fma_f32 v[36:37], v[14:15], v[44:45], v[22:23]
	v_pk_fma_f32 v[44:45], v[12:13], v[56:57], v[20:21]
	v_bfe_u32 v58, v37, 16, 1
	v_bfe_u32 v56, v44, 16, 1
	v_add3_u32 v56, v44, v56, s35
	v_bfe_u32 v57, v45, 16, 1
	v_lshrrev_b32_e32 v56, 16, v56
	v_add3_u32 v57, v45, v57, s35
	v_and_or_b32 v56, v57, s54, v56
	v_bfe_u32 v57, v36, 16, 1
	v_add3_u32 v57, v36, v57, s35
	v_lshrrev_b32_e32 v57, 16, v57
	v_add3_u32 v58, v37, v58, s35
	v_and_or_b32 v57, v58, s54, v57
	global_store_dwordx2 v[52:53], v[56:57], off offset:-512
	v_pk_mul_f32 v[46:47], v[46:47], v[60:61] op_sel_hi:[1,0]
	v_pk_mul_f32 v[56:57], v[32:33], v[60:61] op_sel_hi:[1,0]
	v_pk_fma_f32 v[32:33], v[26:27], v[46:47], v[30:31]
	v_pk_fma_f32 v[46:47], v[24:25], v[56:57], v[28:29]
	v_bfe_u32 v58, v33, 16, 1
	v_bfe_u32 v56, v46, 16, 1
	v_add3_u32 v56, v46, v56, s35
	v_bfe_u32 v57, v47, 16, 1
	v_lshrrev_b32_e32 v56, 16, v56
	v_add3_u32 v57, v47, v57, s35
	v_and_or_b32 v56, v57, s54, v56
	v_bfe_u32 v57, v32, 16, 1
	v_add3_u32 v57, v32, v57, s35
	v_lshrrev_b32_e32 v57, 16, v57
	v_add3_u32 v58, v33, v58, s35
	v_and_or_b32 v57, v58, s54, v57
	global_store_dwordx2 v[52:53], v[56:57], off
	v_add_u32_e32 v60, 0, v50
	ds_read_b128 v[56:59], v60
	ds_read_b128 v[66:69], v60 offset:1024
	ds_read_b128 v[70:73], v60 offset:2048
	ds_read_b128 v[74:77], v60 offset:3072
	v_mbcnt_lo_u32_b32 v78, -1, 0
	v_mbcnt_hi_u32_b32 v78, -1, v78
	v_mbcnt_lo_u32_b32 v83, -1, 0
	v_mbcnt_hi_u32_b32 v83, -1, v83
	v_mbcnt_lo_u32_b32 v98, -1, 0
	v_mbcnt_hi_u32_b32 v98, -1, v98
	v_mbcnt_lo_u32_b32 v99, -1, 0
	v_mbcnt_hi_u32_b32 v99, -1, v99
	v_mbcnt_lo_u32_b32 v100, -1, 0
	v_mbcnt_hi_u32_b32 v100, -1, v100
	s_waitcnt lgkmcnt(3)
	v_mov_b32_e32 v87, v57
	v_lshlrev_b32_e32 v82, 2, v78
	ds_read_b128 v[78:81], v60 offset:4096
	v_xor_b32_e32 v101, 8, v82
	v_lshlrev_b32_e32 v82, 2, v83
	v_xor_b32_e32 v102, 16, v82
	ds_read_b128 v[82:85], v60 offset:5120
	s_waitcnt lgkmcnt(1)
	v_mov_b32_e32 v86, v78
	v_pk_mul_f32 v[94:95], v[38:39], v[86:87]
	v_mov_b32_e32 v86, v80
	v_mov_b32_e32 v87, v59
	v_pk_mul_f32 v[96:97], v[34:35], v[86:87]
	v_pk_mov_b32 v[56:57], v[78:79], v[56:57] op_sel:[1,0]
	v_pk_mov_b32 v[58:59], v[80:81], v[58:59] op_sel:[1,0]
	v_pk_fma_f32 v[56:57], v[38:39], v[56:57], v[94:95] op_sel:[1,0,0] op_sel_hi:[0,1,1]
	v_pk_fma_f32 v[58:59], v[34:35], v[58:59], v[96:97] op_sel:[1,0,0] op_sel_hi:[0,1,1]
	v_pk_add_f32 v[56:57], v[56:57], v[58:59]
	s_waitcnt lgkmcnt(0)
	v_mov_b32_e32 v58, v82
	v_mov_b32_e32 v59, v67
	v_pk_mul_f32 v[58:59], v[42:43], v[58:59]
	v_pk_mov_b32 v[66:67], v[82:83], v[66:67] op_sel:[1,0]
	ds_read_b128 v[86:89], v60 offset:6144
	ds_read_b128 v[90:93], v60 offset:7168
	v_pk_fma_f32 v[58:59], v[42:43], v[66:67], v[58:59] op_sel:[1,0,0] op_sel_hi:[0,1,1]
	v_mov_b32_e32 v66, v84
	v_mov_b32_e32 v67, v69
	v_pk_mul_f32 v[66:67], v[40:41], v[66:67]
	v_pk_mov_b32 v[68:69], v[84:85], v[68:69] op_sel:[1,0]
	v_pk_add_f32 v[56:57], v[56:57], 0 op_sel_hi:[1,0]
	v_pk_fma_f32 v[66:67], v[40:41], v[68:69], v[66:67] op_sel:[1,0,0] op_sel_hi:[0,1,1]
	v_pk_add_f32 v[58:59], v[58:59], v[66:67]
	s_waitcnt lgkmcnt(1)
	v_pk_mov_b32 v[66:67], v[86:87], v[70:71] op_sel:[1,0]
	v_pk_add_f32 v[56:57], v[56:57], v[58:59]
	v_mov_b32_e32 v58, v86
	v_mov_b32_e32 v59, v71
	v_pk_mul_f32 v[58:59], v[44:45], v[58:59]
	v_pk_mov_b32 v[68:69], v[88:89], v[72:73] op_sel:[1,0]
	v_pk_fma_f32 v[58:59], v[44:45], v[66:67], v[58:59] op_sel:[1,0,0] op_sel_hi:[0,1,1]
	v_mov_b32_e32 v66, v88
	v_mov_b32_e32 v67, v73
	v_pk_mul_f32 v[66:67], v[36:37], v[66:67]
	v_mbcnt_lo_u32_b32 v103, -1, 0
	v_mbcnt_hi_u32_b32 v103, -1, v103
	v_pk_fma_f32 v[66:67], v[36:37], v[68:69], v[66:67] op_sel:[1,0,0] op_sel_hi:[0,1,1]
	v_pk_add_f32 v[58:59], v[58:59], v[66:67]
	s_waitcnt lgkmcnt(0)
; __device__ __forceinline__ float shx(float v, int o) { const int l = lane_now(); return __int_as_float(__builtin_amdgcn_ds_bpermute((l ^ o) << 2, __float_as_int(v))); }
; #define LAS __attribute__((address_space(3)))
; __device__ __forceinline__ float wave_sum(float v) {
; #pragma unroll
;     for (int o = 1; o < 64; o <<= 1) v += shx(v, o);
;     return v;
; template <int SRC, int EXTRA, bool OUT8 = false> ...
;     ...
;             for (int e = 0; e < 8; ++e) { float a = 0.f;
; #pragma unroll
;                 for (int j = 0; j < 4; ++j) { const f32x4 w = *(const LAS f32x4*)(w8s + e * 1024 + 256 * j + 4 * lane); a += (v[j].x * w.x + v[j].y * w.y) + (v[j].z * w.z + v[j].w * w.w); }
;                 d[e] = wave_sum(a); }
	v_pk_mov_b32 v[66:67], v[90:91], v[74:75] op_sel:[1,0]
	v_pk_add_f32 v[56:57], v[56:57], v[58:59]
	v_mov_b32_e32 v58, v90
	v_mov_b32_e32 v59, v75
	v_pk_mul_f32 v[58:59], v[46:47], v[58:59]
	v_pk_mov_b32 v[68:69], v[92:93], v[76:77] op_sel:[1,0]
	v_pk_fma_f32 v[58:59], v[46:47], v[66:67], v[58:59] op_sel:[1,0,0] op_sel_hi:[0,1,1]
	v_mov_b32_e32 v66, v92
	v_mov_b32_e32 v67, v77
	v_pk_mul_f32 v[66:67], v[32:33], v[66:67]
	v_lshlrev_b32_e32 v103, 2, v103
	v_pk_fma_f32 v[66:67], v[32:33], v[68:69], v[66:67] op_sel:[1,0,0] op_sel_hi:[0,1,1]
	v_pk_add_f32 v[58:59], v[58:59], v[66:67]
	v_xor_b32_e32 v103, 4, v103
	v_pk_add_f32 v[56:57], v[56:57], v[58:59]
	s_nop 1
	v_mov_b32_dpp v59, v57 quad_perm:[1,0,3,2] row_mask:0xf bank_mask:0xf
	s_nop 1
	v_mov_b32_dpp v58, v56 quad_perm:[1,0,3,2] row_mask:0xf bank_mask:0xf
	v_pk_add_f32 v[56:57], v[56:57], v[58:59]
	s_nop 1
	v_mov_b32_dpp v59, v57 quad_perm:[2,3,0,1] row_mask:0xf bank_mask:0xf
	s_nop 1
	v_mov_b32_dpp v58, v56 quad_perm:[2,3,0,1] row_mask:0xf bank_mask:0xf
	v_pk_add_f32 v[56:57], v[56:57], v[58:59]
	s_nop 1
	v_mov_b32_dpp v59, v57 row_shl:4 row_mask:0xf bank_mask:0x5
	v_mov_b32_dpp v59, v57 row_shr:4 row_mask:0xf bank_mask:0xa
	s_nop 1
	v_mov_b32_dpp v58, v56 row_shl:4 row_mask:0xf bank_mask:0x5
	v_mov_b32_dpp v58, v56 row_shr:4 row_mask:0xf bank_mask:0xa
	v_pk_add_f32 v[56:57], v[56:57], v[58:59]
	s_nop 1
	v_mov_b32_dpp v59, v57 row_ror:8 row_mask:0xf bank_mask:0xf
	s_nop 1
	v_mov_b32_dpp v58, v56 row_ror:8 row_mask:0xf bank_mask:0xf
	v_pk_add_f32 v[56:57], v[56:57], v[58:59]
	v_mov_b32_e32 v59, v57
	v_mov_b32_e32 v120, v57
	s_nop 1
	v_permlane16_swap_b32_e32 v59, v120
	v_cndmask_b32_e64 v59, v120, v59, s[98:99]
	v_mov_b32_e32 v58, v56
	v_mov_b32_e32 v120, v56
	s_nop 1
	v_permlane16_swap_b32_e32 v58, v120
	v_cndmask_b32_e64 v58, v120, v58, s[98:99]
	v_pk_add_f32 v[56:57], v[56:57], v[58:59]
	ds_read_b128 v[66:69], v60 offset:8192
	ds_read_b128 v[70:73], v60 offset:9216
	v_mov_b32_e32 v59, v57
	v_mov_b32_e32 v120, v57
	s_nop 1
	v_permlane32_swap_b32_e32 v59, v120
	v_cndmask_b32_e64 v59, v120, v59, s[100:101]
	s_waitcnt lgkmcnt(1)
	v_mul_f32_e32 v65, v39, v67
	v_fmac_f32_e32 v65, v38, v66
	v_mul_f32_e32 v66, v35, v69
	v_fmac_f32_e32 v66, v34, v68
	v_add_f32_e32 v65, v65, v66
	s_waitcnt lgkmcnt(0)
	v_mul_f32_e32 v71, v43, v71
	ds_read_b128 v[66:69], v60 offset:10240
	v_fmac_f32_e32 v71, v42, v70
	v_mul_f32_e32 v70, v41, v73
	v_fmac_f32_e32 v70, v40, v72
	v_add_f32_e32 v65, 0, v65
	v_add_f32_e32 v70, v71, v70
	v_add_f32_e32 v65, v65, v70
	ds_read_b128 v[70:73], v60 offset:11264
	s_waitcnt lgkmcnt(1)
	v_mul_f32_e32 v67, v45, v67
	v_fmac_f32_e32 v67, v44, v66
	v_mul_f32_e32 v66, v37, v69
	v_fmac_f32_e32 v66, v36, v68
	v_add_f32_e32 v66, v67, v66
	v_add_f32_e32 v65, v65, v66
	s_waitcnt lgkmcnt(0)
	v_mul_f32_e32 v66, v47, v71
	v_mul_f32_e32 v67, v33, v73
	v_fmac_f32_e32 v66, v46, v70
	v_fmac_f32_e32 v67, v32, v72
	v_add_f32_e32 v66, v66, v67
	v_add_f32_e32 v65, v65, v66
	ds_read_b128 v[66:69], v60 offset:12288
	s_nop 1
	v_mov_b32_dpp v79, v65 quad_perm:[1,0,3,2] row_mask:0xf bank_mask:0xf
	ds_read_b128 v[70:73], v60 offset:13312
	s_waitcnt lgkmcnt(1)
	v_mul_f32_e32 v67, v39, v67
	v_fmac_f32_e32 v67, v38, v66
	v_mul_f32_e32 v66, v35, v69
	v_fmac_f32_e32 v66, v34, v68
	v_add_f32_e32 v66, v67, v66
	s_waitcnt lgkmcnt(0)
	v_mul_f32_e32 v71, v43, v71
	v_add_f32_e32 v80, 0, v66
	v_fmac_f32_e32 v71, v42, v70
	v_mul_f32_e32 v70, v41, v73
	ds_read_b128 v[66:69], v60 offset:14336
	v_fmac_f32_e32 v70, v40, v72
	v_add_f32_e32 v70, v71, v70
	v_add_f32_e32 v80, v80, v70
	ds_read_b128 v[70:73], v60 offset:15360
	s_waitcnt lgkmcnt(1)
	v_mul_f32_e32 v67, v45, v67
	v_fmac_f32_e32 v67, v44, v66
	v_mul_f32_e32 v66, v37, v69
	v_fmac_f32_e32 v66, v36, v68
	v_add_f32_e32 v66, v67, v66
	s_waitcnt lgkmcnt(0)
	v_mul_f32_e32 v67, v47, v71
	v_mul_f32_e32 v68, v33, v73
	v_fmac_f32_e32 v67, v46, v70
	v_fmac_f32_e32 v68, v32, v72
	v_add_f32_e32 v66, v80, v66
	v_add_f32_e32 v67, v67, v68
	v_add_f32_e32 v66, v66, v67
	s_nop 1
	v_mov_b32_dpp v67, v66 quad_perm:[1,0,3,2] row_mask:0xf bank_mask:0xf
	v_add_f32_e32 v65, v65, v79
	s_nop 1
	v_mov_b32_dpp v68, v65 quad_perm:[2,3,0,1] row_mask:0xf bank_mask:0xf
	v_mov_b32_e32 v58, v56
	v_mov_b32_e32 v120, v56
	s_nop 1
	v_permlane32_swap_b32_e32 v58, v120
	v_cndmask_b32_e64 v58, v120, v58, s[100:101]
	v_add_f32_e32 v66, v66, v67
	v_add_f32_e32 v65, v65, v68
	s_nop 1
	v_mov_b32_dpp v67, v66 quad_perm:[2,3,0,1] row_mask:0xf bank_mask:0xf
	s_nop 1
	v_mov_b32_dpp v68, v65 row_shl:4 row_mask:0xf bank_mask:0x5
	v_mov_b32_dpp v68, v65 row_shr:4 row_mask:0xf bank_mask:0xa
	v_add_f32_e32 v66, v66, v67
	v_add_f32_e32 v65, v65, v68
	s_nop 1
	v_mov_b32_dpp v67, v66 row_shl:4 row_mask:0xf bank_mask:0x5
	v_mov_b32_dpp v67, v66 row_shr:4 row_mask:0xf bank_mask:0xa
	s_nop 1
	v_mov_b32_dpp v68, v65 row_ror:8 row_mask:0xf bank_mask:0xf
	v_add_f32_e32 v66, v66, v67
	v_add_f32_e32 v65, v65, v68
	s_nop 1
	v_mov_b32_dpp v67, v66 row_ror:8 row_mask:0xf bank_mask:0xf
	v_mov_b32_e32 v68, v65
	v_mov_b32_e32 v120, v65
	s_nop 1
	v_permlane16_swap_b32_e32 v68, v120
	v_cndmask_b32_e64 v68, v120, v68, s[98:99]
	v_add_f32_e32 v67, v66, v67
	v_add_f32_e32 v65, v65, v68
	v_mov_b32_e32 v69, v67
	v_mov_b32_e32 v120, v67
	s_nop 1
	v_permlane16_swap_b32_e32 v69, v120
	v_cndmask_b32_e64 v69, v120, v69, s[98:99]
	ds_read_b128 v[70:73], v60 offset:16384
	ds_read_b128 v[74:77], v60 offset:17408
	v_add_f32_e32 v67, v67, v69
	s_waitcnt lgkmcnt(1)
	v_mul_f32_e32 v69, v39, v71
	v_fmac_f32_e32 v69, v38, v70
	v_mul_f32_e32 v70, v35, v73
	v_fmac_f32_e32 v70, v34, v72
	v_add_f32_e32 v69, v69, v70
	s_waitcnt lgkmcnt(0)
; __device__ __forceinline__ float shx(float v, int o) { const int l = lane_now(); return __int_as_float(__builtin_amdgcn_ds_bpermute((l ^ o) << 2, __float_as_int(v))); }
; #define LAS __attribute__((address_space(3)))
; __device__ __forceinline__ float wave_sum(float v) {
; #pragma unroll
;     for (int o = 1; o < 64; o <<= 1) v += shx(v, o);
;     return v;
; template <int SRC, int EXTRA, bool OUT8 = false> ...
;     ...
;             for (int e = 0; e < 8; ++e) { float a = 0.f;
; #pragma unroll
;                 for (int j = 0; j < 4; ++j) { const f32x4 w = *(const LAS f32x4*)(w8s + e * 1024 + 256 * j + 4 * lane); a += (v[j].x * w.x + v[j].y * w.y) + (v[j].z * w.z + v[j].w * w.w); }
;                 d[e] = wave_sum(a); }
	v_mul_f32_e32 v75, v43, v75
	ds_read_b128 v[70:73], v60 offset:18432
	v_fmac_f32_e32 v75, v42, v74
	v_mul_f32_e32 v74, v41, v77
	v_fmac_f32_e32 v74, v40, v76
	v_add_f32_e32 v69, 0, v69
	v_add_f32_e32 v74, v75, v74
	v_add_f32_e32 v69, v69, v74
	ds_read_b128 v[74:77], v60 offset:19456
	s_waitcnt lgkmcnt(1)
	v_mul_f32_e32 v71, v45, v71
	v_fmac_f32_e32 v71, v44, v70
	v_mul_f32_e32 v70, v37, v73
	v_fmac_f32_e32 v70, v36, v72
	v_add_f32_e32 v70, v71, v70
	v_add_f32_e32 v69, v69, v70
	s_waitcnt lgkmcnt(0)
	v_mul_f32_e32 v70, v47, v75
	v_mul_f32_e32 v71, v33, v77
	v_fmac_f32_e32 v70, v46, v74
	v_fmac_f32_e32 v71, v32, v76
	v_add_f32_e32 v70, v70, v71
	v_add_f32_e32 v69, v69, v70
	ds_read_b128 v[70:73], v60 offset:20480
	s_nop 1
	v_mov_b32_dpp v83, v69 quad_perm:[1,0,3,2] row_mask:0xf bank_mask:0xf
	ds_read_b128 v[74:77], v60 offset:21504
	s_waitcnt lgkmcnt(1)
	v_mul_f32_e32 v71, v39, v71
	v_fmac_f32_e32 v71, v38, v70
	v_mul_f32_e32 v70, v35, v73
	v_fmac_f32_e32 v70, v34, v72
	v_add_f32_e32 v70, v71, v70
	s_waitcnt lgkmcnt(0)
	v_mul_f32_e32 v75, v43, v75
	v_add_f32_e32 v84, 0, v70
	v_fmac_f32_e32 v75, v42, v74
	v_mul_f32_e32 v74, v41, v77
	ds_read_b128 v[70:73], v60 offset:22528
	v_fmac_f32_e32 v74, v40, v76
	v_add_f32_e32 v74, v75, v74
	v_add_f32_e32 v84, v84, v74
	ds_read_b128 v[74:77], v60 offset:23552
	s_waitcnt lgkmcnt(1)
	v_mul_f32_e32 v71, v45, v71
	v_fmac_f32_e32 v71, v44, v70
	v_mul_f32_e32 v70, v37, v73
	v_fmac_f32_e32 v70, v36, v72
	v_add_f32_e32 v70, v71, v70
	s_waitcnt lgkmcnt(0)
	v_mul_f32_e32 v71, v47, v75
	v_mul_f32_e32 v72, v33, v77
	v_fmac_f32_e32 v71, v46, v74
	v_fmac_f32_e32 v72, v32, v76
	v_add_f32_e32 v70, v84, v70
	v_add_f32_e32 v71, v71, v72
	v_add_f32_e32 v70, v70, v71
	s_nop 1
	v_mov_b32_dpp v71, v70 quad_perm:[1,0,3,2] row_mask:0xf bank_mask:0xf
	v_add_f32_e32 v69, v69, v83
	s_nop 1
	v_mov_b32_dpp v72, v69 quad_perm:[2,3,0,1] row_mask:0xf bank_mask:0xf
	v_add_f32_e32 v70, v70, v71
	s_nop 1
	v_mov_b32_dpp v71, v70 quad_perm:[2,3,0,1] row_mask:0xf bank_mask:0xf
	v_add_f32_e32 v69, v69, v72
	s_nop 1
	v_mov_b32_dpp v72, v69 row_shl:4 row_mask:0xf bank_mask:0x5
	v_mov_b32_dpp v72, v69 row_shr:4 row_mask:0xf bank_mask:0xa
	v_add_f32_e32 v70, v70, v71
	v_mov_b32_e32 v66, v65
	v_mov_b32_e32 v120, v65
	s_nop 1
	v_permlane32_swap_b32_e32 v66, v120
	v_cndmask_b32_e64 v66, v120, v66, s[100:101]
	s_nop 1
	v_mov_b32_dpp v71, v70 row_shl:4 row_mask:0xf bank_mask:0x5
	v_mov_b32_dpp v71, v70 row_shr:4 row_mask:0xf bank_mask:0xa
	v_add_f32_e32 v69, v69, v72
	s_nop 1
	v_mov_b32_dpp v72, v69 row_ror:8 row_mask:0xf bank_mask:0xf
	v_add_f32_e32 v70, v70, v71
	v_mov_b32_e32 v68, v67
	v_mov_b32_e32 v120, v67
	s_nop 1
	v_permlane32_swap_b32_e32 v68, v120
	v_cndmask_b32_e64 v68, v120, v68, s[100:101]
	s_nop 1
	v_mov_b32_dpp v71, v70 row_ror:8 row_mask:0xf bank_mask:0xf
	v_add_f32_e32 v69, v69, v72
	v_mov_b32_e32 v72, v69
	v_mov_b32_e32 v120, v69
	s_nop 1
	v_permlane16_swap_b32_e32 v72, v120
	v_cndmask_b32_e64 v72, v120, v72, s[98:99]
	v_add_f32_e32 v71, v70, v71
	v_add_f32_e32 v69, v69, v72
	v_mov_b32_e32 v73, v71
	v_mov_b32_e32 v120, v71
	s_nop 1
	v_permlane16_swap_b32_e32 v73, v120
	v_cndmask_b32_e64 v73, v120, v73, s[98:99]
	ds_read_b128 v[74:77], v60 offset:24576
	ds_read_b128 v[78:81], v60 offset:25600
	v_add_f32_e32 v71, v71, v73
	s_waitcnt lgkmcnt(1)
	v_mul_f32_e32 v73, v39, v75
	v_fmac_f32_e32 v73, v38, v74
	v_mul_f32_e32 v74, v35, v77
	v_fmac_f32_e32 v74, v34, v76
	v_add_f32_e32 v73, v73, v74
	s_waitcnt lgkmcnt(0)
	v_mul_f32_e32 v79, v43, v79
	ds_read_b128 v[74:77], v60 offset:26624
	v_fmac_f32_e32 v79, v42, v78
	v_mul_f32_e32 v78, v41, v81
	v_fmac_f32_e32 v78, v40, v80
	v_add_f32_e32 v73, 0, v73
	v_add_f32_e32 v78, v79, v78
	v_add_f32_e32 v73, v73, v78
	ds_read_b128 v[78:81], v60 offset:27648
	s_waitcnt lgkmcnt(1)
	v_mul_f32_e32 v75, v45, v75
	v_fmac_f32_e32 v75, v44, v74
	v_mul_f32_e32 v74, v37, v77
	v_fmac_f32_e32 v74, v36, v76
	v_add_f32_e32 v74, v75, v74
	v_add_f32_e32 v73, v73, v74
	s_waitcnt lgkmcnt(0)
	v_mul_f32_e32 v74, v47, v79
	v_mul_f32_e32 v75, v33, v81
	v_fmac_f32_e32 v74, v46, v78
	v_fmac_f32_e32 v75, v32, v80
	v_add_f32_e32 v74, v74, v75
	v_add_f32_e32 v73, v73, v74
	v_mbcnt_lo_u32_b32 v82, -1, 0
	v_mbcnt_hi_u32_b32 v82, -1, v82
	v_mbcnt_lo_u32_b32 v83, -1, 0
	v_mbcnt_hi_u32_b32 v83, -1, v83
	v_mbcnt_lo_u32_b32 v84, -1, 0
	v_mbcnt_hi_u32_b32 v84, -1, v84
	v_mbcnt_lo_u32_b32 v85, -1, 0
	v_mbcnt_hi_u32_b32 v85, -1, v85
	v_mbcnt_lo_u32_b32 v86, -1, 0
	v_mbcnt_hi_u32_b32 v86, -1, v86
	ds_read_b128 v[74:77], v60 offset:28672
	s_nop 1
	v_mov_b32_dpp v87, v73 quad_perm:[1,0,3,2] row_mask:0xf bank_mask:0xf
	ds_read_b128 v[78:81], v60 offset:29696
	s_waitcnt lgkmcnt(1)
	v_mul_f32_e32 v39, v39, v75
	v_mul_f32_e32 v35, v35, v77
	v_fmac_f32_e32 v39, v38, v74
	v_fmac_f32_e32 v35, v34, v76
	ds_read_b128 v[74:77], v60 offset:30720
	v_add_f32_e32 v34, v39, v35
	s_waitcnt lgkmcnt(1)
	v_mul_f32_e32 v35, v43, v79
	v_mul_f32_e32 v38, v41, v81
	v_fmac_f32_e32 v35, v42, v78
	v_fmac_f32_e32 v38, v40, v80
	v_add_f32_e32 v35, v35, v38
	ds_read_b128 v[38:41], v60 offset:31744
	v_add_f32_e32 v34, 0, v34
	v_add_f32_e32 v34, v34, v35
	s_waitcnt lgkmcnt(1)
	v_mul_f32_e32 v35, v45, v75
	v_mul_f32_e32 v37, v37, v77
	v_fmac_f32_e32 v35, v44, v74
	v_fmac_f32_e32 v37, v36, v76
	v_add_f32_e32 v35, v35, v37
	v_add_f32_e32 v34, v34, v35
	s_waitcnt lgkmcnt(0)
; #define LAS __attribute__((address_space(3)))
; template <int SRC, int EXTRA, bool OUT8 = false> ...
;     ...
;             for (int e = 0; e < 8; ++e) { float a = 0.f;
; #pragma unroll
;                 for (int j = 0; j < 4; ++j) { const f32x4 w = *(const LAS f32x4*)(w8s + e * 1024 + 256 * j + 4 * lane); a += (v[j].x * w.x + v[j].y * w.y) + (v[j].z * w.z + v[j].w * w.w); }
;                 d[e] = wave_sum(a); }
;             if (EXTRA == 1) {
;                 float x = d[0];
; #pragma unroll
;                 for (int e = 1; e < 8; ++e) x = (lane == e) ? d[e] : x;
;                 if (lane < 8) { x += bf8[lane]; const float ls = (x >= 0.f) ? -log1pf(__expf(-x)) : (x - log1pf(__expf(x))); logf[(size_t)lane * M + row] = ls; }
;             } else {
;                 int i0 = 0; float v0 = d[0];
; #pragma unroll
;                 for (int e = 1; e < 8; ++e) if (d[e] > v0) { v0 = d[e]; i0 = e; }
;                 int i1 = -1; float v1 = -INFINITY;
; #pragma unroll
;                 for (int e = 0; e < 8; ++e) if (e != i0 && d[e] > v1) { v1 = d[e]; i1 = e; }
;                 if (lane == 0) { const float w0 = 1.f / (1.f + __expf(v1 - v0)); eidx[row] = i0 | (i1 << 8); gwout[2 * row] = w0; gwout[2 * row + 1] = 1.f - w0;
;                     atomicAdd((unsigned*)&lcnt[i0], 1u); atomicAdd((unsigned*)&lcnt[i1], 1u); }
	v_mul_f32_e32 v35, v47, v39
	v_mul_f32_e32 v33, v33, v41
	v_fmac_f32_e32 v35, v46, v38
	v_fmac_f32_e32 v33, v32, v40
	v_add_f32_e32 v32, v35, v33
	v_add_f32_e32 v32, v34, v32
	s_nop 1
	v_mov_b32_dpp v33, v32 quad_perm:[1,0,3,2] row_mask:0xf bank_mask:0xf
	v_add_f32_e32 v34, v73, v87
	s_nop 1
	v_mov_b32_dpp v35, v34 quad_perm:[2,3,0,1] row_mask:0xf bank_mask:0xf
	v_add_f32_e32 v32, v32, v33
	s_nop 1
	v_mov_b32_dpp v33, v32 quad_perm:[2,3,0,1] row_mask:0xf bank_mask:0xf
	v_add_f32_e32 v34, v34, v35
	s_nop 1
	v_mov_b32_dpp v35, v34 row_shl:4 row_mask:0xf bank_mask:0x5
	v_mov_b32_dpp v35, v34 row_shr:4 row_mask:0xf bank_mask:0xa
	v_add_f32_e32 v32, v32, v33
	s_nop 1
	v_mov_b32_dpp v33, v32 row_shl:4 row_mask:0xf bank_mask:0x5
	v_mov_b32_dpp v33, v32 row_shr:4 row_mask:0xf bank_mask:0xa
	v_add_f32_e32 v34, v34, v35
	s_nop 1
	v_mov_b32_dpp v35, v34 row_ror:8 row_mask:0xf bank_mask:0xf
	v_add_f32_e32 v32, v32, v33
	v_mov_b32_e32 v70, v69
	v_mov_b32_e32 v120, v69
	s_nop 1
	v_permlane32_swap_b32_e32 v70, v120
	v_cndmask_b32_e64 v70, v120, v70, s[100:101]
	s_nop 1
	v_mov_b32_dpp v33, v32 row_ror:8 row_mask:0xf bank_mask:0xf
	v_add_f32_e32 v34, v34, v35
	v_mov_b32_e32 v35, v34
	v_mov_b32_e32 v120, v34
	s_nop 1
	v_permlane16_swap_b32_e32 v35, v120
	v_cndmask_b32_e64 v35, v120, v35, s[98:99]
	v_add_f32_e32 v36, v32, v33
	v_mov_b32_e32 v37, v36
	v_mov_b32_e32 v120, v36
	s_nop 1
	v_permlane16_swap_b32_e32 v37, v120
	v_cndmask_b32_e64 v37, v120, v37, s[98:99]
	v_add_f32_e32 v32, v34, v35
	v_add_f32_e32 v34, v36, v37
	v_mov_b32_e32 v72, v71
	v_mov_b32_e32 v120, v71
	s_nop 1
	v_permlane32_swap_b32_e32 v72, v120
	v_cndmask_b32_e64 v72, v120, v72, s[100:101]
	v_mov_b32_e32 v33, v32
	v_mov_b32_e32 v120, v32
	s_nop 1
	v_permlane32_swap_b32_e32 v33, v120
	v_cndmask_b32_e64 v33, v120, v33, s[100:101]
	v_mov_b32_e32 v35, v34
	v_mov_b32_e32 v120, v34
	s_nop 1
	v_permlane32_swap_b32_e32 v35, v120
	v_cndmask_b32_e64 v35, v120, v35, s[100:101]
	s_and_saveexec_b64 s[48:49], s[10:11]
	s_cbranch_execz .LBB0_1895
	v_add_f32_e32 v34, v34, v35
	v_add_f32_e32 v35, v32, v33
	v_pk_add_f32 v[32:33], v[56:57], v[58:59]
	v_add_f32_e32 v39, v65, v66
	v_cmp_gt_f32_e32 vcc, v32, v33
	v_add_f32_e32 v38, v67, v68
	v_add_f32_e32 v37, v69, v70
	v_cndmask_b32_e32 v40, v33, v32, vcc
	v_cmp_gt_f32_e64 s[12:13], v39, v40
	v_add_f32_e32 v36, v71, v72
	v_cndmask_b32_e64 v41, 0, 1, vcc
	v_cndmask_b32_e64 v40, v40, v39, s[12:13]
	v_cmp_gt_f32_e64 s[14:15], v38, v40
	v_cndmask_b32_e64 v41, v41, 2, s[12:13]
	v_cmp_nlg_f32_e64 s[24:25], s55, v33
	v_cndmask_b32_e64 v40, v40, v38, s[14:15]
	v_cmp_gt_f32_e64 s[16:17], v37, v40
	v_cndmask_b32_e64 v41, v41, 3, s[14:15]
	s_ashr_i32 s39, s38, 31
	v_cndmask_b32_e64 v40, v40, v37, s[16:17]
	v_cmp_gt_f32_e64 s[18:19], v36, v40
	v_cndmask_b32_e64 v41, v41, 4, s[16:17]
	s_nop 0
	v_cndmask_b32_e64 v40, v40, v36, s[18:19]
	v_cmp_gt_f32_e64 s[20:21], v35, v40
	v_cndmask_b32_e64 v41, v41, 5, s[18:19]
	s_nop 0
	v_cndmask_b32_e64 v40, v40, v35, s[20:21]
	v_cndmask_b32_e64 v41, v41, 6, s[20:21]
	v_cmp_ngt_f32_e32 vcc, v34, v40
	s_and_b64 s[26:27], s[20:21], vcc
	s_nop 0
	v_cndmask_b32_e32 v41, 7, v41, vcc
	v_cmp_eq_u32_e64 s[22:23], 0, v41
	s_or_b64 s[22:23], s[22:23], s[24:25]
	v_cmp_ne_u32_e64 s[20:21], 1, v41
	v_cndmask_b32_e64 v33, v33, v64, s[22:23]
	v_cmp_gt_f32_e64 s[24:25], v32, v33
	s_and_b64 s[20:21], s[20:21], s[24:25]
	v_cndmask_b32_e64 v32, v33, v32, s[20:21]
	v_cmp_ne_u32_e64 s[18:19], 2, v41
	v_cmp_gt_f32_e64 s[24:25], v39, v32
	s_and_b64 s[18:19], s[18:19], s[24:25]
	v_cndmask_b32_e64 v32, v32, v39, s[18:19]
	v_cmp_ne_u32_e64 s[16:17], 3, v41
	v_cmp_gt_f32_e64 s[24:25], v38, v32
	s_and_b64 s[16:17], s[16:17], s[24:25]
	v_cndmask_b32_e64 v32, v32, v38, s[16:17]
	v_cmp_ne_u32_e64 s[14:15], 4, v41
	v_cmp_gt_f32_e64 s[24:25], v37, v32
	s_and_b64 s[14:15], s[14:15], s[24:25]
	v_cndmask_b32_e64 v32, v32, v37, s[14:15]
	v_cmp_ne_u32_e64 s[12:13], 5, v41
	v_cmp_gt_f32_e64 s[24:25], v36, v32
	s_and_b64 s[12:13], s[12:13], s[24:25]
	v_cndmask_b32_e64 v32, v32, v36, s[12:13]
	v_cmp_ngt_f32_e64 s[24:25], v35, v32
	s_or_b64 s[24:25], s[26:27], s[24:25]
	v_cndmask_b32_e64 v33, 0, -1, s[22:23]
	v_cndmask_b32_e64 v32, v35, v32, s[24:25]
	v_cmp_gt_f32_e64 s[26:27], v34, v32
	s_and_b64 s[26:27], vcc, s[26:27]
	v_cndmask_b32_e64 v33, v33, 1, s[20:21]
	v_cndmask_b32_e64 v32, v32, v34, s[26:27]
	v_cndmask_b32_e32 v34, v34, v40, vcc
	v_sub_f32_e32 v32, v32, v34
	v_mul_f32_e32 v32, 0x3fb8aa3b, v32
	v_exp_f32_e32 v32, v32
	v_cndmask_b32_e64 v33, v33, 2, s[18:19]
	v_cndmask_b32_e64 v33, v33, 3, s[16:17]
	v_cndmask_b32_e64 v33, v33, 4, s[14:15]
	v_add_f32_e32 v32, 1.0, v32
	v_div_scale_f32 v34, s[14:15], v32, v32, 1.0
	v_rcp_f32_e32 v35, v34
	v_cndmask_b32_e64 v33, v33, 5, s[12:13]
	v_cndmask_b32_e64 v33, 6, v33, s[24:25]
	v_cndmask_b32_e64 v36, v33, 7, s[26:27]
	v_fma_f32 v33, -v34, v35, 1.0
	v_fmac_f32_e32 v35, v33, v35
	v_div_scale_f32 v33, vcc, 1.0, v32, 1.0
	v_mul_f32_e32 v37, v33, v35
	v_fma_f32 v38, -v34, v37, v33
	v_fmac_f32_e32 v37, v38, v35
	v_fma_f32 v33, -v34, v37, v33
	v_div_fmas_f32 v33, v33, v35, v37
	s_lshl_b64 s[12:13], s[38:39], 2
	v_div_fixup_f32 v32, v33, v32, 1.0
	v_lshl_add_u32 v33, v36, 8, v41
	s_add_u32 s12, s51, s12
	global_store_dword v51, v33, s[40:41]
	s_addc_u32 s13, s52, s13
	v_sub_f32_e32 v33, 1.0, v32
	global_store_dwordx2 v51, v[32:33], s[12:13]
	v_lshl_add_u32 v32, v41, 2, 0
	ds_add_u32 v32, v63 offset:32768
	v_lshl_add_u32 v32, v36, 2, 0
	ds_add_u32 v32, v63 offset:32768
	s_branch .LBB0_1895

; __device__ __forceinline__ int mk_tid(int wv) { return (wv << 6) | lane_now(); }
; #define LAS __attribute__((address_space(3)))
; __device__ __forceinline__ unsigned char* karg_ws() { return *(unsigned char* const __attribute__((address_space(4)))*)(karg_base() + 192); }
; template <int SEL> __global__ void __launch_bounds__(NWAVES * 64, 2) fwd_kernel(Args args) {
;     extern __shared__ __attribute__((aligned(16))) unsigned char lds[];
;     LAS unsigned char* ldsp = (LAS unsigned char*)lds;
;     const int G = gridDim.x, bx = blockIdx.x; const int vcu = (G % 8 == 0) ? (bx % 8) * (G / 8) + bx / 8 : bx;
;     const int wv = __builtin_amdgcn_readfirstlane((int)threadIdx.x >> 6);
;     if constexpr (SEL < 0) { const int t0_ = mk_tid(wv); if (t0_ < 2) ((volatile LAS unsigned*)(ldsp + attn_body::LDS_BYTES))[t0_] = 0u; __syncthreads();
;         (void)xcd_barrier_post((unsigned*)(karg_ws() + WS_BAR), (volatile LAS unsigned*)(ldsp + attn_body::LDS_BYTES), wv); }
	.amdhsa_kernel _Z10fwd_kernelILin1EEv4Args
		.amdhsa_group_segment_fixed_size 0
		.amdhsa_private_segment_fixed_size 0
		.amdhsa_kernarg_size 456
		.amdhsa_user_sgpr_count 2
		.amdhsa_user_sgpr_dispatch_ptr 0
		.amdhsa_user_sgpr_queue_ptr 0
		.amdhsa_user_sgpr_kernarg_segment_ptr 1
		.amdhsa_user_sgpr_dispatch_id 0
		.amdhsa_user_sgpr_kernarg_preload_length 0
		.amdhsa_user_sgpr_kernarg_preload_offset 0
		.amdhsa_user_sgpr_private_segment_size 0
		.amdhsa_uses_dynamic_stack 0
		.amdhsa_enable_private_segment 0
		.amdhsa_system_sgpr_workgroup_id_x 1
		.amdhsa_system_sgpr_workgroup_id_y 0
		.amdhsa_system_sgpr_workgroup_id_z 0
		.amdhsa_system_sgpr_workgroup_info 0
		.amdhsa_system_vgpr_workitem_id 2
		.amdhsa_next_free_vgpr 256
		.amdhsa_next_free_sgpr 102
		.amdhsa_accum_offset 256
		.amdhsa_reserve_vcc 1
		.amdhsa_float_round_mode_32 0
		.amdhsa_float_round_mode_16_64 0
		.amdhsa_float_denorm_mode_32 3
		.amdhsa_float_denorm_mode_16_64 3
		.amdhsa_dx10_clamp 1
		.amdhsa_ieee_mode 1
		.amdhsa_fp16_overflow 0
		.amdhsa_tg_split 0
		.amdhsa_exception_fp_ieee_invalid_op 0
		.amdhsa_exception_fp_denorm_src 0
		.amdhsa_exception_fp_ieee_div_zero 0
		.amdhsa_exception_fp_ieee_overflow 0
		.amdhsa_exception_fp_ieee_underflow 0
		.amdhsa_exception_fp_ieee_inexact 0
		.amdhsa_exception_int_div_zero 0
	.end_amdhsa_kernel

; __device__ __forceinline__ int mk_tid(int wv) { return (wv << 6) | lane_now(); }
; #define LAS __attribute__((address_space(3)))
; __device__ __forceinline__ unsigned char* karg_ws() { return *(unsigned char* const __attribute__((address_space(4)))*)(karg_base() + 192); }
; template <int SEL> __global__ void __launch_bounds__(NWAVES * 64, 2) fwd_kernel(Args args) {
;     extern __shared__ __attribute__((aligned(16))) unsigned char lds[];
;     LAS unsigned char* ldsp = (LAS unsigned char*)lds;
;     const int G = gridDim.x, bx = blockIdx.x; const int vcu = (G % 8 == 0) ? (bx % 8) * (G / 8) + bx / 8 : bx;
;     const int wv = __builtin_amdgcn_readfirstlane((int)threadIdx.x >> 6);
;     if constexpr (SEL < 0) { const int t0_ = mk_tid(wv); if (t0_ < 2) ((volatile LAS unsigned*)(ldsp + attn_body::LDS_BYTES))[t0_] = 0u; __syncthreads();
;         (void)xcd_barrier_post((unsigned*)(karg_ws() + WS_BAR), (volatile LAS unsigned*)(ldsp + attn_body::LDS_BYTES), wv); }
amdhsa.kernels:
  - .agpr_count:     0
    .args:
      - .offset:         0
        .size:           200
        .value_kind:     by_value
      - .offset:         200
        .size:           4
        .value_kind:     hidden_block_count_x
      - .offset:         204
        .size:           4
        .value_kind:     hidden_block_count_y
      - .offset:         208
        .size:           4
        .value_kind:     hidden_block_count_z
      - .offset:         212
        .size:           2
        .value_kind:     hidden_group_size_x
      - .offset:         214
        .size:           2
        .value_kind:     hidden_group_size_y
      - .offset:         216
        .size:           2
        .value_kind:     hidden_group_size_z
      - .offset:         218
        .size:           2
        .value_kind:     hidden_remainder_x
      - .offset:         220
        .size:           2
        .value_kind:     hidden_remainder_y
      - .offset:         222
        .size:           2
        .value_kind:     hidden_remainder_z
      - .offset:         240
        .size:           8
        .value_kind:     hidden_global_offset_x
      - .offset:         248
        .size:           8
        .value_kind:     hidden_global_offset_y
      - .offset:         256
        .size:           8
        .value_kind:     hidden_global_offset_z
      - .offset:         264
        .size:           2
        .value_kind:     hidden_grid_dims
      - .offset:         288
        .size:           8
        .value_kind:     hidden_multigrid_sync_arg
      - .offset:         320
        .size:           4
        .value_kind:     hidden_dynamic_lds_size
    .group_segment_fixed_size: 0
    .kernarg_segment_align: 8
    .kernarg_segment_size: 456
    .language:       OpenCL C
    .language_version:
      - 2
      - 0
    .max_flat_workgroup_size: 512
    .name:           _Z10fwd_kernelILin1EEv4Args
    .private_segment_fixed_size: 0
    .sgpr_count:     108
    .sgpr_spill_count: 6
    .symbol:         _Z10fwd_kernelILin1EEv4Args.kd
    .uniform_work_group_size: 1
    .uses_dynamic_stack: false
    .vgpr_count:     256
    .vgpr_spill_count: 0
    .wavefront_size: 64
